# layer-1 weight conversion: hand-written batched loop (4 tiles of 64x64 per iteration, 32 loads in flight per wave, double-buffered LDS, one barrier per iteration) replaces the 7 large conv_T loops
# speedup vs baseline: 1.0211x; 1.0211x over previous
; DI int ltid() { int t = threadIdx.x; asm volatile("" : "+v"(t)); return t; }
; DI int lbid() { int b = blockIdx.x; asm volatile("" : "+s"(b)); return b; }
; template <class Map>
; DI void conv_T(bf16_t* __restrict__ dst, const float* __restrict__ src, int K, int ldsrc, int nphys, Map map, const float* __restrict__ kscale, float* tile) {
;   const int tid = ltid(), ntn = nphys >> 6, ntiles = (K >> 6) * ntn;
;   for (int tl = lbid(); tl < ntiles; tl += gridDim.x) {
;     const int k0 = (tl / ntn) << 6, n0 = (tl % ntn) << 6;
;     const int nn = tid & 63, sc = map(n0 + nn);
; #pragma unroll
;     for (int i = 0; i < 8; ++i) { const int kk = i * 8 + (tid >> 6);
;       float v = sc >= 0 ? __builtin_nontemporal_load(&src[(size_t)(k0 + kk) * ldsrc + sc]) : 0.f;
;       if (kscale) v *= kscale[k0 + kk];
;       tile[kk * 65 + nn] = v; }
; DI void convert_layer(const Params& p, int l, float* tile) {
;     ...
;   conv_T((bf16_t*)(ws + O_WIN), p.w_in + (size_t)l * 2048 * NIN, 2048, NIN, NPHYS, MapIn{}, nullptr, tile);
.LBB0_2124:
	s_or_b64 exec, exec, s[0:1]
	v_mov_b32_e32 v0, v248
	s_mov_b32 s4, s85
	s_barrier
	v_readlane_b32 s18, v252, 21
	v_readlane_b32 s19, v252, 22
	v_readlane_b32 s20, v252, 40
	v_readlane_b32 s21, v251, 63
	v_lshrrev_b32_e32 v36, 6, v248
	v_and_b32_e32 v37, 63, v248
	v_mul_u32_u24_e32 v30, 0x104, v36
	v_lshl_add_u32 v30, v37, 2, v30
	v_add_u32_e32 v31, 0x10400, v30
	v_and_b32_e32 v36, 7, v248
	v_lshrrev_b32_e32 v37, 3, v248
	v_mul_u32_u24_e32 v32, 0x820, v36
	v_lshl_add_u32 v32, v37, 2, v32
	v_add_u32_e32 v33, 0x10400, v32
	v_readlane_b32 s22, v249, 16
	v_readlane_b32 s23, v249, 17
	s_sub_u32 s22, s22, 0xa0
	s_subb_u32 s23, s23, 0
	s_load_dwordx2 s[4:5], s[22:23], 0x20
	s_waitcnt lgkmcnt(0)
	s_add_u32 s4, s4, 0x70d0000
	s_addc_u32 s5, s5, 0
	s_add_u32 s6, s18, 0x0
	s_addc_u32 s7, s19, 0
	v_lshrrev_b32_e32 v36, 6, v248
	v_and_b32_e32 v37, 63, v248
	v_mov_b32_e32 v38, 0xe1a0
	v_mul_u32_u24_e32 v34, v36, v38
	v_lshl_add_u32 v34, v37, 2, v34
	v_lshrrev_b32_e32 v36, 3, v248
	v_and_b32_e32 v37, 7, v248
	v_mov_b32_e32 v38, 0x1000
	v_mul_u32_u24_e32 v35, v36, v38
	v_lshl_add_u32 v35, v37, 4, v35
	s_mov_b32 s8, s20
	s_cmp_ge_u32 s8, 0x1c00
	s_cbranch_scc1 .Lcv_win_l1_end
.Lcv_win_l1_loop:
	s_mov_b32 s12, s8
	s_mul_i32 s13, s12, 0x2493
	s_lshr_b32 s13, s13, 21
	s_mul_i32 s14, s13, 224
	s_sub_u32 s14, s12, s14
	s_mul_i32 s15, s13, 0x386800
	s_lshl_b32 s16, s14, 8
	s_cmp_ge_u32 s14, 40
	s_cselect_b32 s12, 0x140, 0
	s_cmp_ge_u32 s14, 80
	s_cselect_b32 s12, 0x1a0, s12
	s_add_u32 s16, s16, s12
	s_add_u32 s15, s15, s16
	s_add_u32 s10, s4, s15
	s_addc_u32 s11, s5, 0
	global_load_dword v40, v34, s[10:11] nt
	s_add_u32 s10, s10, 0x70d00
	s_addc_u32 s11, s11, 0
	global_load_dword v41, v34, s[10:11] nt
	s_add_u32 s10, s10, 0x70d00
	s_addc_u32 s11, s11, 0
	global_load_dword v42, v34, s[10:11] nt
	s_add_u32 s10, s10, 0x70d00
	s_addc_u32 s11, s11, 0
	global_load_dword v43, v34, s[10:11] nt
	s_add_u32 s10, s10, 0x70d00
	s_addc_u32 s11, s11, 0
	global_load_dword v44, v34, s[10:11] nt
	s_add_u32 s10, s10, 0x70d00
	s_addc_u32 s11, s11, 0
	global_load_dword v45, v34, s[10:11] nt
	s_add_u32 s10, s10, 0x70d00
	s_addc_u32 s11, s11, 0
	global_load_dword v46, v34, s[10:11] nt
	s_add_u32 s10, s10, 0x70d00
	s_addc_u32 s11, s11, 0
	global_load_dword v47, v34, s[10:11] nt
	s_mul_i32 s12, s21, 1
	s_add_u32 s12, s12, s8
	s_cmp_ge_u32 s12, 0x1c00
	s_cbranch_scc1 .Lcv_win_l1_p0_ld_done
	s_mul_i32 s12, s21, 1
	s_add_u32 s12, s12, s8
	s_mul_i32 s13, s12, 0x2493
	s_lshr_b32 s13, s13, 21
	s_mul_i32 s14, s13, 224
	s_sub_u32 s14, s12, s14
	s_mul_i32 s15, s13, 0x386800
	s_lshl_b32 s16, s14, 8
	s_cmp_ge_u32 s14, 40
	s_cselect_b32 s12, 0x140, 0
	s_cmp_ge_u32 s14, 80
	s_cselect_b32 s12, 0x1a0, s12
	s_add_u32 s16, s16, s12
	s_add_u32 s15, s15, s16
	s_add_u32 s10, s4, s15
	s_addc_u32 s11, s5, 0
	global_load_dword v48, v34, s[10:11] nt
	s_add_u32 s10, s10, 0x70d00
	s_addc_u32 s11, s11, 0
	global_load_dword v49, v34, s[10:11] nt
	s_add_u32 s10, s10, 0x70d00
	s_addc_u32 s11, s11, 0
	global_load_dword v50, v34, s[10:11] nt
	s_add_u32 s10, s10, 0x70d00
	s_addc_u32 s11, s11, 0
	global_load_dword v51, v34, s[10:11] nt
	s_add_u32 s10, s10, 0x70d00
	s_addc_u32 s11, s11, 0
	global_load_dword v52, v34, s[10:11] nt
	s_add_u32 s10, s10, 0x70d00
	s_addc_u32 s11, s11, 0
	global_load_dword v53, v34, s[10:11] nt
	s_add_u32 s10, s10, 0x70d00
	s_addc_u32 s11, s11, 0
	global_load_dword v54, v34, s[10:11] nt
	s_add_u32 s10, s10, 0x70d00
	s_addc_u32 s11, s11, 0
	global_load_dword v55, v34, s[10:11] nt
	s_mul_i32 s12, s21, 2
	s_add_u32 s12, s12, s8
	s_cmp_ge_u32 s12, 0x1c00
	s_cbranch_scc1 .Lcv_win_l1_p0_ld_done
	s_mul_i32 s12, s21, 2
	s_add_u32 s12, s12, s8
	s_mul_i32 s13, s12, 0x2493
	s_lshr_b32 s13, s13, 21
	s_mul_i32 s14, s13, 224
	s_sub_u32 s14, s12, s14
	s_mul_i32 s15, s13, 0x386800
	s_lshl_b32 s16, s14, 8
	s_cmp_ge_u32 s14, 40
	s_cselect_b32 s12, 0x140, 0
	s_cmp_ge_u32 s14, 80
	s_cselect_b32 s12, 0x1a0, s12
	s_add_u32 s16, s16, s12
	s_add_u32 s15, s15, s16
	s_add_u32 s10, s4, s15
	s_addc_u32 s11, s5, 0
	global_load_dword v56, v34, s[10:11] nt
	s_add_u32 s10, s10, 0x70d00
	s_addc_u32 s11, s11, 0
	global_load_dword v57, v34, s[10:11] nt
	s_add_u32 s10, s10, 0x70d00
	s_addc_u32 s11, s11, 0
	global_load_dword v58, v34, s[10:11] nt
	s_add_u32 s10, s10, 0x70d00
	s_addc_u32 s11, s11, 0
	global_load_dword v59, v34, s[10:11] nt
	s_add_u32 s10, s10, 0x70d00
	s_addc_u32 s11, s11, 0
	global_load_dword v60, v34, s[10:11] nt
	s_add_u32 s10, s10, 0x70d00
	s_addc_u32 s11, s11, 0
	global_load_dword v61, v34, s[10:11] nt
	s_add_u32 s10, s10, 0x70d00
	s_addc_u32 s11, s11, 0
	global_load_dword v62, v34, s[10:11] nt
	s_add_u32 s10, s10, 0x70d00
	s_addc_u32 s11, s11, 0
	global_load_dword v63, v34, s[10:11] nt
	s_mul_i32 s12, s21, 3
	s_add_u32 s12, s12, s8
	s_cmp_ge_u32 s12, 0x1c00
	s_cbranch_scc1 .Lcv_win_l1_p0_ld_done
	s_mul_i32 s12, s21, 3
	s_add_u32 s12, s12, s8
	s_mul_i32 s13, s12, 0x2493
	s_lshr_b32 s13, s13, 21
	s_mul_i32 s14, s13, 224
	s_sub_u32 s14, s12, s14
	s_mul_i32 s15, s13, 0x386800
	s_lshl_b32 s16, s14, 8
	s_cmp_ge_u32 s14, 40
	s_cselect_b32 s12, 0x140, 0
	s_cmp_ge_u32 s14, 80
	s_cselect_b32 s12, 0x1a0, s12
	s_add_u32 s16, s16, s12
	s_add_u32 s15, s15, s16
	s_add_u32 s10, s4, s15
	s_addc_u32 s11, s5, 0
	global_load_dword v64, v34, s[10:11] nt
	s_add_u32 s10, s10, 0x70d00
	s_addc_u32 s11, s11, 0
	global_load_dword v65, v34, s[10:11] nt
	s_add_u32 s10, s10, 0x70d00
	s_addc_u32 s11, s11, 0
	global_load_dword v66, v34, s[10:11] nt
	s_add_u32 s10, s10, 0x70d00
	s_addc_u32 s11, s11, 0
	global_load_dword v67, v34, s[10:11] nt
	s_add_u32 s10, s10, 0x70d00
	s_addc_u32 s11, s11, 0
	global_load_dword v68, v34, s[10:11] nt
	s_add_u32 s10, s10, 0x70d00
	s_addc_u32 s11, s11, 0
	global_load_dword v69, v34, s[10:11] nt
	s_add_u32 s10, s10, 0x70d00
	s_addc_u32 s11, s11, 0
	global_load_dword v70, v34, s[10:11] nt
	s_add_u32 s10, s10, 0x70d00
	s_addc_u32 s11, s11, 0
	global_load_dword v71, v34, s[10:11] nt
; DI unsigned cvtpk(float lo, float hi) { unsigned r; asm volatile("v_cvt_pk_bf16_f32 %0, %1, %2" : "=v"(r) : "v"(lo), "v"(hi)); return r; }
; template <class Map>
; DI void conv_T(bf16_t* __restrict__ dst, const float* __restrict__ src, int K, int ldsrc, int nphys, Map map, const float* __restrict__ kscale, float* tile) {
;     ...
;     const int nn = tid & 63, sc = map(n0 + nn);
; #pragma unroll
;     for (int i = 0; i < 8; ++i) { const int kk = i * 8 + (tid >> 6);
;       float v = sc >= 0 ? __builtin_nontemporal_load(&src[(size_t)(k0 + kk) * ldsrc + sc]) : 0.f;
;       if (kscale) v *= kscale[k0 + kk];
;       tile[kk * 65 + nn] = v; }
;     __syncthreads();
;     const int np = tid >> 3, ks = tid & 7;
;     float v[8];
; #pragma unroll
;     for (int j = 0; j < 8; ++j) v[j] = tile[(ks * 8 + j) * 65 + np];
;     u32x4 w = {cvtpk(v[0], v[1]), cvtpk(v[2], v[3]), cvtpk(v[4], v[5]), cvtpk(v[6], v[7])};
;     *(u32x4*)(dst + (size_t)(n0 + np) * K + k0 + ks * 8) = w;
.Lcv_win_l1_p0_ld_done:
	s_waitcnt vmcnt(0)
	ds_write_b32 v30, v40
	ds_write_b32 v30, v41 offset:2080
	ds_write_b32 v30, v42 offset:4160
	ds_write_b32 v30, v43 offset:6240
	ds_write_b32 v30, v44 offset:8320
	ds_write_b32 v30, v45 offset:10400
	ds_write_b32 v30, v46 offset:12480
	ds_write_b32 v30, v47 offset:14560
	s_mul_i32 s12, s21, 1
	s_add_u32 s12, s12, s8
	s_cmp_ge_u32 s12, 0x1c00
	s_cbranch_scc1 .Lcv_win_l1_p0_wr_done
	ds_write_b32 v30, v48 offset:16640
	ds_write_b32 v30, v49 offset:18720
	ds_write_b32 v30, v50 offset:20800
	ds_write_b32 v30, v51 offset:22880
	ds_write_b32 v30, v52 offset:24960
	ds_write_b32 v30, v53 offset:27040
	ds_write_b32 v30, v54 offset:29120
	ds_write_b32 v30, v55 offset:31200
	s_mul_i32 s12, s21, 2
	s_add_u32 s12, s12, s8
	s_cmp_ge_u32 s12, 0x1c00
	s_cbranch_scc1 .Lcv_win_l1_p0_wr_done
	ds_write_b32 v30, v56 offset:33280
	ds_write_b32 v30, v57 offset:35360
	ds_write_b32 v30, v58 offset:37440
	ds_write_b32 v30, v59 offset:39520
	ds_write_b32 v30, v60 offset:41600
	ds_write_b32 v30, v61 offset:43680
	ds_write_b32 v30, v62 offset:45760
	ds_write_b32 v30, v63 offset:47840
	s_mul_i32 s12, s21, 3
	s_add_u32 s12, s12, s8
	s_cmp_ge_u32 s12, 0x1c00
	s_cbranch_scc1 .Lcv_win_l1_p0_wr_done
	ds_write_b32 v30, v64 offset:49920
	ds_write_b32 v30, v65 offset:52000
	ds_write_b32 v30, v66 offset:54080
	ds_write_b32 v30, v67 offset:56160
	ds_write_b32 v30, v68 offset:58240
	ds_write_b32 v30, v69 offset:60320
	ds_write_b32 v30, v70 offset:62400
	ds_write_b32 v30, v71 offset:64480
.Lcv_win_l1_p0_wr_done:
	s_waitcnt lgkmcnt(0)
	s_barrier
	ds_read_b32 v40, v32
	ds_read_b32 v41, v32 offset:260
	ds_read_b32 v42, v32 offset:520
	ds_read_b32 v43, v32 offset:780
	ds_read_b32 v44, v32 offset:1040
	ds_read_b32 v45, v32 offset:1300
	ds_read_b32 v46, v32 offset:1560
	ds_read_b32 v47, v32 offset:1820
	s_mul_i32 s12, s21, 1
	s_add_u32 s12, s12, s8
	s_cmp_ge_u32 s12, 0x1c00
	s_cbranch_scc1 .Lcv_win_l1_p0_rd_done
	ds_read_b32 v48, v32 offset:16640
	ds_read_b32 v49, v32 offset:16900
	ds_read_b32 v50, v32 offset:17160
	ds_read_b32 v51, v32 offset:17420
	ds_read_b32 v52, v32 offset:17680
	ds_read_b32 v53, v32 offset:17940
	ds_read_b32 v54, v32 offset:18200
	ds_read_b32 v55, v32 offset:18460
	s_mul_i32 s12, s21, 2
	s_add_u32 s12, s12, s8
	s_cmp_ge_u32 s12, 0x1c00
	s_cbranch_scc1 .Lcv_win_l1_p0_rd_done
	ds_read_b32 v56, v32 offset:33280
	ds_read_b32 v57, v32 offset:33540
	ds_read_b32 v58, v32 offset:33800
	ds_read_b32 v59, v32 offset:34060
	ds_read_b32 v60, v32 offset:34320
	ds_read_b32 v61, v32 offset:34580
	ds_read_b32 v62, v32 offset:34840
	ds_read_b32 v63, v32 offset:35100
	s_mul_i32 s12, s21, 3
	s_add_u32 s12, s12, s8
	s_cmp_ge_u32 s12, 0x1c00
	s_cbranch_scc1 .Lcv_win_l1_p0_rd_done
	ds_read_b32 v64, v32 offset:49920
	ds_read_b32 v65, v32 offset:50180
	ds_read_b32 v66, v32 offset:50440
	ds_read_b32 v67, v32 offset:50700
	ds_read_b32 v68, v32 offset:50960
	ds_read_b32 v69, v32 offset:51220
	ds_read_b32 v70, v32 offset:51480
	ds_read_b32 v71, v32 offset:51740
.Lcv_win_l1_p0_rd_done:
	s_waitcnt lgkmcnt(0)
	s_mov_b32 s12, s8
	s_mul_i32 s13, s12, 0x2493
	s_lshr_b32 s13, s13, 21
	s_mul_i32 s14, s13, 224
	s_sub_u32 s14, s12, s14
	s_mul_i32 s15, s14, 0x40000
	s_lshl_b32 s16, s13, 7
	s_add_u32 s15, s15, s16
	s_add_u32 s10, s6, s15
	s_addc_u32 s11, s7, 0
	v_cvt_pk_bf16_f32 v72, v40, v41
	v_cvt_pk_bf16_f32 v73, v42, v43
	v_cvt_pk_bf16_f32 v74, v44, v45
	v_cvt_pk_bf16_f32 v75, v46, v47
	global_store_dwordx4 v35, v[72:75], s[10:11]
	s_mul_i32 s12, s21, 1
	s_add_u32 s12, s12, s8
	s_cmp_ge_u32 s12, 0x1c00
	s_cbranch_scc1 .Lcv_win_l1_p0_st_done
	s_mul_i32 s12, s21, 1
	s_add_u32 s12, s12, s8
	s_mul_i32 s13, s12, 0x2493
	s_lshr_b32 s13, s13, 21
	s_mul_i32 s14, s13, 224
	s_sub_u32 s14, s12, s14
	s_mul_i32 s15, s14, 0x40000
	s_lshl_b32 s16, s13, 7
	s_add_u32 s15, s15, s16
	s_add_u32 s10, s6, s15
	s_addc_u32 s11, s7, 0
	v_cvt_pk_bf16_f32 v76, v48, v49
	v_cvt_pk_bf16_f32 v77, v50, v51
	v_cvt_pk_bf16_f32 v78, v52, v53
	v_cvt_pk_bf16_f32 v79, v54, v55
	global_store_dwordx4 v35, v[76:79], s[10:11]
	s_mul_i32 s12, s21, 2
	s_add_u32 s12, s12, s8
	s_cmp_ge_u32 s12, 0x1c00
	s_cbranch_scc1 .Lcv_win_l1_p0_st_done
	s_mul_i32 s12, s21, 2
	s_add_u32 s12, s12, s8
	s_mul_i32 s13, s12, 0x2493
	s_lshr_b32 s13, s13, 21
	s_mul_i32 s14, s13, 224
	s_sub_u32 s14, s12, s14
	s_mul_i32 s15, s14, 0x40000
	s_lshl_b32 s16, s13, 7
	s_add_u32 s15, s15, s16
	s_add_u32 s10, s6, s15
	s_addc_u32 s11, s7, 0
	v_cvt_pk_bf16_f32 v80, v56, v57
	v_cvt_pk_bf16_f32 v81, v58, v59
	v_cvt_pk_bf16_f32 v82, v60, v61
	v_cvt_pk_bf16_f32 v83, v62, v63
	global_store_dwordx4 v35, v[80:83], s[10:11]
	s_mul_i32 s12, s21, 3
	s_add_u32 s12, s12, s8
	s_cmp_ge_u32 s12, 0x1c00
	s_cbranch_scc1 .Lcv_win_l1_p0_st_done
	s_mul_i32 s12, s21, 3
	s_add_u32 s12, s12, s8
	s_mul_i32 s13, s12, 0x2493
	s_lshr_b32 s13, s13, 21
	s_mul_i32 s14, s13, 224
	s_sub_u32 s14, s12, s14
	s_mul_i32 s15, s14, 0x40000
	s_lshl_b32 s16, s13, 7
	s_add_u32 s15, s15, s16
	s_add_u32 s10, s6, s15
	s_addc_u32 s11, s7, 0
	v_cvt_pk_bf16_f32 v84, v64, v65
	v_cvt_pk_bf16_f32 v85, v66, v67
	v_cvt_pk_bf16_f32 v86, v68, v69
	v_cvt_pk_bf16_f32 v87, v70, v71
	global_store_dwordx4 v35, v[84:87], s[10:11]
; DI int lbid() { int b = blockIdx.x; asm volatile("" : "+s"(b)); return b; }
; template <class Map>
; DI void conv_T(bf16_t* __restrict__ dst, const float* __restrict__ src, int K, int ldsrc, int nphys, Map map, const float* __restrict__ kscale, float* tile) {
;     ...
;   for (int tl = lbid(); tl < ntiles; tl += gridDim.x) {
;     const int k0 = (tl / ntn) << 6, n0 = (tl % ntn) << 6;
;     const int nn = tid & 63, sc = map(n0 + nn);
; #pragma unroll
;     for (int i = 0; i < 8; ++i) { const int kk = i * 8 + (tid >> 6);
;       float v = sc >= 0 ? __builtin_nontemporal_load(&src[(size_t)(k0 + kk) * ldsrc + sc]) : 0.f;
;       if (kscale) v *= kscale[k0 + kk];
;       tile[kk * 65 + nn] = v; }
.Lcv_win_l1_p0_st_done:
	s_lshl_b32 s12, s21, 2
	s_add_u32 s8, s8, s12
	s_cmp_ge_u32 s8, 0x1c00
	s_cbranch_scc1 .Lcv_win_l1_end
	s_mov_b32 s12, s8
	s_mul_i32 s13, s12, 0x2493
	s_lshr_b32 s13, s13, 21
	s_mul_i32 s14, s13, 224
	s_sub_u32 s14, s12, s14
	s_mul_i32 s15, s13, 0x386800
	s_lshl_b32 s16, s14, 8
	s_cmp_ge_u32 s14, 40
	s_cselect_b32 s12, 0x140, 0
	s_cmp_ge_u32 s14, 80
	s_cselect_b32 s12, 0x1a0, s12
	s_add_u32 s16, s16, s12
	s_add_u32 s15, s15, s16
	s_add_u32 s10, s4, s15
	s_addc_u32 s11, s5, 0
	global_load_dword v40, v34, s[10:11] nt
	s_add_u32 s10, s10, 0x70d00
	s_addc_u32 s11, s11, 0
	global_load_dword v41, v34, s[10:11] nt
	s_add_u32 s10, s10, 0x70d00
	s_addc_u32 s11, s11, 0
	global_load_dword v42, v34, s[10:11] nt
	s_add_u32 s10, s10, 0x70d00
	s_addc_u32 s11, s11, 0
	global_load_dword v43, v34, s[10:11] nt
	s_add_u32 s10, s10, 0x70d00
	s_addc_u32 s11, s11, 0
	global_load_dword v44, v34, s[10:11] nt
	s_add_u32 s10, s10, 0x70d00
	s_addc_u32 s11, s11, 0
	global_load_dword v45, v34, s[10:11] nt
	s_add_u32 s10, s10, 0x70d00
	s_addc_u32 s11, s11, 0
	global_load_dword v46, v34, s[10:11] nt
	s_add_u32 s10, s10, 0x70d00
	s_addc_u32 s11, s11, 0
	global_load_dword v47, v34, s[10:11] nt
	s_mul_i32 s12, s21, 1
	s_add_u32 s12, s12, s8
	s_cmp_ge_u32 s12, 0x1c00
	s_cbranch_scc1 .Lcv_win_l1_p1_ld_done
	s_mul_i32 s12, s21, 1
	s_add_u32 s12, s12, s8
	s_mul_i32 s13, s12, 0x2493
	s_lshr_b32 s13, s13, 21
	s_mul_i32 s14, s13, 224
	s_sub_u32 s14, s12, s14
	s_mul_i32 s15, s13, 0x386800
	s_lshl_b32 s16, s14, 8
	s_cmp_ge_u32 s14, 40
	s_cselect_b32 s12, 0x140, 0
	s_cmp_ge_u32 s14, 80
	s_cselect_b32 s12, 0x1a0, s12
	s_add_u32 s16, s16, s12
	s_add_u32 s15, s15, s16
	s_add_u32 s10, s4, s15
	s_addc_u32 s11, s5, 0
	global_load_dword v48, v34, s[10:11] nt
	s_add_u32 s10, s10, 0x70d00
	s_addc_u32 s11, s11, 0
	global_load_dword v49, v34, s[10:11] nt
	s_add_u32 s10, s10, 0x70d00
	s_addc_u32 s11, s11, 0
	global_load_dword v50, v34, s[10:11] nt
	s_add_u32 s10, s10, 0x70d00
	s_addc_u32 s11, s11, 0
	global_load_dword v51, v34, s[10:11] nt
	s_add_u32 s10, s10, 0x70d00
	s_addc_u32 s11, s11, 0
	global_load_dword v52, v34, s[10:11] nt
	s_add_u32 s10, s10, 0x70d00
	s_addc_u32 s11, s11, 0
	global_load_dword v53, v34, s[10:11] nt
	s_add_u32 s10, s10, 0x70d00
	s_addc_u32 s11, s11, 0
	global_load_dword v54, v34, s[10:11] nt
	s_add_u32 s10, s10, 0x70d00
	s_addc_u32 s11, s11, 0
	global_load_dword v55, v34, s[10:11] nt
	s_mul_i32 s12, s21, 2
	s_add_u32 s12, s12, s8
	s_cmp_ge_u32 s12, 0x1c00
	s_cbranch_scc1 .Lcv_win_l1_p1_ld_done
	s_mul_i32 s12, s21, 2
	s_add_u32 s12, s12, s8
	s_mul_i32 s13, s12, 0x2493
	s_lshr_b32 s13, s13, 21
	s_mul_i32 s14, s13, 224
	s_sub_u32 s14, s12, s14
	s_mul_i32 s15, s13, 0x386800
	s_lshl_b32 s16, s14, 8
	s_cmp_ge_u32 s14, 40
	s_cselect_b32 s12, 0x140, 0
	s_cmp_ge_u32 s14, 80
	s_cselect_b32 s12, 0x1a0, s12
	s_add_u32 s16, s16, s12
	s_add_u32 s15, s15, s16
	s_add_u32 s10, s4, s15
	s_addc_u32 s11, s5, 0
	global_load_dword v56, v34, s[10:11] nt
	s_add_u32 s10, s10, 0x70d00
	s_addc_u32 s11, s11, 0
	global_load_dword v57, v34, s[10:11] nt
	s_add_u32 s10, s10, 0x70d00
	s_addc_u32 s11, s11, 0
	global_load_dword v58, v34, s[10:11] nt
	s_add_u32 s10, s10, 0x70d00
	s_addc_u32 s11, s11, 0
	global_load_dword v59, v34, s[10:11] nt
	s_add_u32 s10, s10, 0x70d00
	s_addc_u32 s11, s11, 0
	global_load_dword v60, v34, s[10:11] nt
	s_add_u32 s10, s10, 0x70d00
	s_addc_u32 s11, s11, 0
	global_load_dword v61, v34, s[10:11] nt
	s_add_u32 s10, s10, 0x70d00
	s_addc_u32 s11, s11, 0
	global_load_dword v62, v34, s[10:11] nt
	s_add_u32 s10, s10, 0x70d00
	s_addc_u32 s11, s11, 0
	global_load_dword v63, v34, s[10:11] nt
	s_mul_i32 s12, s21, 3
	s_add_u32 s12, s12, s8
	s_cmp_ge_u32 s12, 0x1c00
	s_cbranch_scc1 .Lcv_win_l1_p1_ld_done
	s_mul_i32 s12, s21, 3
	s_add_u32 s12, s12, s8
	s_mul_i32 s13, s12, 0x2493
	s_lshr_b32 s13, s13, 21
	s_mul_i32 s14, s13, 224
	s_sub_u32 s14, s12, s14
	s_mul_i32 s15, s13, 0x386800
	s_lshl_b32 s16, s14, 8
	s_cmp_ge_u32 s14, 40
	s_cselect_b32 s12, 0x140, 0
	s_cmp_ge_u32 s14, 80
	s_cselect_b32 s12, 0x1a0, s12
	s_add_u32 s16, s16, s12
	s_add_u32 s15, s15, s16
	s_add_u32 s10, s4, s15
	s_addc_u32 s11, s5, 0
	global_load_dword v64, v34, s[10:11] nt
	s_add_u32 s10, s10, 0x70d00
	s_addc_u32 s11, s11, 0
	global_load_dword v65, v34, s[10:11] nt
	s_add_u32 s10, s10, 0x70d00
	s_addc_u32 s11, s11, 0
	global_load_dword v66, v34, s[10:11] nt
	s_add_u32 s10, s10, 0x70d00
	s_addc_u32 s11, s11, 0
	global_load_dword v67, v34, s[10:11] nt
	s_add_u32 s10, s10, 0x70d00
	s_addc_u32 s11, s11, 0
	global_load_dword v68, v34, s[10:11] nt
	s_add_u32 s10, s10, 0x70d00
	s_addc_u32 s11, s11, 0
	global_load_dword v69, v34, s[10:11] nt
	s_add_u32 s10, s10, 0x70d00
	s_addc_u32 s11, s11, 0
	global_load_dword v70, v34, s[10:11] nt
	s_add_u32 s10, s10, 0x70d00
	s_addc_u32 s11, s11, 0
	global_load_dword v71, v34, s[10:11] nt
; template <class Map>
; DI void conv_T(bf16_t* __restrict__ dst, const float* __restrict__ src, int K, int ldsrc, int nphys, Map map, const float* __restrict__ kscale, float* tile) {
;     ...
;     for (int i = 0; i < 8; ++i) { const int kk = i * 8 + (tid >> 6);
;       float v = sc >= 0 ? __builtin_nontemporal_load(&src[(size_t)(k0 + kk) * ldsrc + sc]) : 0.f;
;       if (kscale) v *= kscale[k0 + kk];
;       tile[kk * 65 + nn] = v; }
;     __syncthreads();
;     const int np = tid >> 3, ks = tid & 7;
;     float v[8];
; #pragma unroll
;     for (int j = 0; j < 8; ++j) v[j] = tile[(ks * 8 + j) * 65 + np];
.Lcv_win_l1_p1_ld_done:
	s_waitcnt vmcnt(0)
	ds_write_b32 v31, v40
	ds_write_b32 v31, v41 offset:2080
	ds_write_b32 v31, v42 offset:4160
	ds_write_b32 v31, v43 offset:6240
	ds_write_b32 v31, v44 offset:8320
	ds_write_b32 v31, v45 offset:10400
	ds_write_b32 v31, v46 offset:12480
	ds_write_b32 v31, v47 offset:14560
	s_mul_i32 s12, s21, 1
	s_add_u32 s12, s12, s8
	s_cmp_ge_u32 s12, 0x1c00
	s_cbranch_scc1 .Lcv_win_l1_p1_wr_done
	ds_write_b32 v31, v48 offset:16640
	ds_write_b32 v31, v49 offset:18720
	ds_write_b32 v31, v50 offset:20800
	ds_write_b32 v31, v51 offset:22880
	ds_write_b32 v31, v52 offset:24960
	ds_write_b32 v31, v53 offset:27040
	ds_write_b32 v31, v54 offset:29120
	ds_write_b32 v31, v55 offset:31200
	s_mul_i32 s12, s21, 2
	s_add_u32 s12, s12, s8
	s_cmp_ge_u32 s12, 0x1c00
	s_cbranch_scc1 .Lcv_win_l1_p1_wr_done
	ds_write_b32 v31, v56 offset:33280
	ds_write_b32 v31, v57 offset:35360
	ds_write_b32 v31, v58 offset:37440
	ds_write_b32 v31, v59 offset:39520
	ds_write_b32 v31, v60 offset:41600
	ds_write_b32 v31, v61 offset:43680
	ds_write_b32 v31, v62 offset:45760
	ds_write_b32 v31, v63 offset:47840
	s_mul_i32 s12, s21, 3
	s_add_u32 s12, s12, s8
	s_cmp_ge_u32 s12, 0x1c00
	s_cbranch_scc1 .Lcv_win_l1_p1_wr_done
	ds_write_b32 v31, v64 offset:49920
	ds_write_b32 v31, v65 offset:52000
	ds_write_b32 v31, v66 offset:54080
	ds_write_b32 v31, v67 offset:56160
	ds_write_b32 v31, v68 offset:58240
	ds_write_b32 v31, v69 offset:60320
	ds_write_b32 v31, v70 offset:62400
	ds_write_b32 v31, v71 offset:64480
.Lcv_win_l1_p1_wr_done:
	s_waitcnt lgkmcnt(0)
	s_barrier
	ds_read_b32 v40, v33
	ds_read_b32 v41, v33 offset:260
	ds_read_b32 v42, v33 offset:520
	ds_read_b32 v43, v33 offset:780
	ds_read_b32 v44, v33 offset:1040
	ds_read_b32 v45, v33 offset:1300
	ds_read_b32 v46, v33 offset:1560
	ds_read_b32 v47, v33 offset:1820
	s_mul_i32 s12, s21, 1
	s_add_u32 s12, s12, s8
	s_cmp_ge_u32 s12, 0x1c00
	s_cbranch_scc1 .Lcv_win_l1_p1_rd_done
	ds_read_b32 v48, v33 offset:16640
	ds_read_b32 v49, v33 offset:16900
	ds_read_b32 v50, v33 offset:17160
	ds_read_b32 v51, v33 offset:17420
	ds_read_b32 v52, v33 offset:17680
	ds_read_b32 v53, v33 offset:17940
	ds_read_b32 v54, v33 offset:18200
	ds_read_b32 v55, v33 offset:18460
	s_mul_i32 s12, s21, 2
	s_add_u32 s12, s12, s8
	s_cmp_ge_u32 s12, 0x1c00
	s_cbranch_scc1 .Lcv_win_l1_p1_rd_done
	ds_read_b32 v56, v33 offset:33280
	ds_read_b32 v57, v33 offset:33540
	ds_read_b32 v58, v33 offset:33800
	ds_read_b32 v59, v33 offset:34060
	ds_read_b32 v60, v33 offset:34320
	ds_read_b32 v61, v33 offset:34580
	ds_read_b32 v62, v33 offset:34840
	ds_read_b32 v63, v33 offset:35100
	s_mul_i32 s12, s21, 3
	s_add_u32 s12, s12, s8
	s_cmp_ge_u32 s12, 0x1c00
	s_cbranch_scc1 .Lcv_win_l1_p1_rd_done
	ds_read_b32 v64, v33 offset:49920
	ds_read_b32 v65, v33 offset:50180
	ds_read_b32 v66, v33 offset:50440
	ds_read_b32 v67, v33 offset:50700
	ds_read_b32 v68, v33 offset:50960
	ds_read_b32 v69, v33 offset:51220
	ds_read_b32 v70, v33 offset:51480
	ds_read_b32 v71, v33 offset:51740

; DI int ltid() { int t = threadIdx.x; asm volatile("" : "+v"(t)); return t; }
; DI int lbid() { int b = blockIdx.x; asm volatile("" : "+s"(b)); return b; }
; template <class Map>
; DI void conv_T(bf16_t* __restrict__ dst, const float* __restrict__ src, int K, int ldsrc, int nphys, Map map, const float* __restrict__ kscale, float* tile) {
;   const int tid = ltid(), ntn = nphys >> 6, ntiles = (K >> 6) * ntn;
;   for (int tl = lbid(); tl < ntiles; tl += gridDim.x) {
;     const int k0 = (tl / ntn) << 6, n0 = (tl % ntn) << 6;
;     const int nn = tid & 63, sc = map(n0 + nn);
; #pragma unroll
;     for (int i = 0; i < 8; ++i) { const int kk = i * 8 + (tid >> 6);
;       float v = sc >= 0 ? __builtin_nontemporal_load(&src[(size_t)(k0 + kk) * ldsrc + sc]) : 0.f;
;       if (kscale) v *= kscale[k0 + kk];
;       tile[kk * 65 + nn] = v; }
; DI void convert_layer(const Params& p, int l, float* tile) {
;     ...
;   for (int r = 0; r < 3; ++r)
;     conv_T((bf16_t*)(ws + O_WBR) + (size_t)r * 2048 * 1024, p.w_br + (size_t)(l * 3 + r) * 1024 * 2048, 1024, 2048, 2048, MapId{0}, nullptr, tile);
.Lcv_win_l1_p1_st_done:
	s_lshl_b32 s12, s21, 2
	s_add_u32 s8, s8, s12
	s_cmp_ge_u32 s8, 0x1c00
	s_cbranch_scc0 .Lcv_win_l1_loop
.Lcv_win_l1_end:
	s_waitcnt lgkmcnt(0)
	s_barrier
	v_readlane_b32 s4, v249, 8
	v_readlane_b32 s5, v249, 9
	s_add_u32 s4, s4, 0x1800000
	s_addc_u32 s5, s5, 0
	s_add_u32 s6, s18, 0x3c00000
	s_addc_u32 s7, s19, 0
	v_lshrrev_b32_e32 v36, 6, v248
	v_and_b32_e32 v37, 63, v248
	v_mov_b32_e32 v38, 0x2000
	v_mul_u32_u24_e32 v34, v36, v38
	v_lshl_add_u32 v34, v37, 2, v34
	v_lshrrev_b32_e32 v36, 3, v248
	v_and_b32_e32 v37, 7, v248
	v_mov_b32_e32 v38, 0x800
	v_mul_u32_u24_e32 v35, v36, v38
	v_lshl_add_u32 v35, v37, 4, v35
	s_mov_b32 s8, s20
	s_cmp_ge_u32 s8, 0x200
	s_cbranch_scc1 .Lcv_wbr0_l1_end
.Lcv_wbr0_l1_loop:
	s_mov_b32 s12, s8
	s_lshr_b32 s13, s12, 5
	s_and_b32 s14, s12, 31
	s_mul_i32 s15, s13, 0x80000
	s_lshl_b32 s16, s14, 8
	s_add_u32 s15, s15, s16
	s_add_u32 s10, s4, s15
	s_addc_u32 s11, s5, 0
	global_load_dword v40, v34, s[10:11] nt
	s_add_u32 s10, s10, 0x10000
	s_addc_u32 s11, s11, 0
	global_load_dword v41, v34, s[10:11] nt
	s_add_u32 s10, s10, 0x10000
	s_addc_u32 s11, s11, 0
	global_load_dword v42, v34, s[10:11] nt
	s_add_u32 s10, s10, 0x10000
	s_addc_u32 s11, s11, 0
	global_load_dword v43, v34, s[10:11] nt
	s_add_u32 s10, s10, 0x10000
	s_addc_u32 s11, s11, 0
	global_load_dword v44, v34, s[10:11] nt
	s_add_u32 s10, s10, 0x10000
	s_addc_u32 s11, s11, 0
	global_load_dword v45, v34, s[10:11] nt
	s_add_u32 s10, s10, 0x10000
	s_addc_u32 s11, s11, 0
	global_load_dword v46, v34, s[10:11] nt
	s_add_u32 s10, s10, 0x10000
	s_addc_u32 s11, s11, 0
	global_load_dword v47, v34, s[10:11] nt
	s_mul_i32 s12, s21, 1
	s_add_u32 s12, s12, s8
	s_cmp_ge_u32 s12, 0x200
	s_cbranch_scc1 .Lcv_wbr0_l1_p0_ld_done
	s_mul_i32 s12, s21, 1
	s_add_u32 s12, s12, s8
	s_lshr_b32 s13, s12, 5
	s_and_b32 s14, s12, 31
	s_mul_i32 s15, s13, 0x80000
	s_lshl_b32 s16, s14, 8
	s_add_u32 s15, s15, s16
	s_add_u32 s10, s4, s15
	s_addc_u32 s11, s5, 0
	global_load_dword v48, v34, s[10:11] nt
	s_add_u32 s10, s10, 0x10000
	s_addc_u32 s11, s11, 0
	global_load_dword v49, v34, s[10:11] nt
	s_add_u32 s10, s10, 0x10000
	s_addc_u32 s11, s11, 0
	global_load_dword v50, v34, s[10:11] nt
	s_add_u32 s10, s10, 0x10000
	s_addc_u32 s11, s11, 0
	global_load_dword v51, v34, s[10:11] nt
	s_add_u32 s10, s10, 0x10000
	s_addc_u32 s11, s11, 0
	global_load_dword v52, v34, s[10:11] nt
	s_add_u32 s10, s10, 0x10000
	s_addc_u32 s11, s11, 0
	global_load_dword v53, v34, s[10:11] nt
	s_add_u32 s10, s10, 0x10000
	s_addc_u32 s11, s11, 0
	global_load_dword v54, v34, s[10:11] nt
	s_add_u32 s10, s10, 0x10000
	s_addc_u32 s11, s11, 0
	global_load_dword v55, v34, s[10:11] nt
	s_mul_i32 s12, s21, 2
	s_add_u32 s12, s12, s8
	s_cmp_ge_u32 s12, 0x200
	s_cbranch_scc1 .Lcv_wbr0_l1_p0_ld_done
	s_mul_i32 s12, s21, 2
	s_add_u32 s12, s12, s8
	s_lshr_b32 s13, s12, 5
	s_and_b32 s14, s12, 31
	s_mul_i32 s15, s13, 0x80000
	s_lshl_b32 s16, s14, 8
	s_add_u32 s15, s15, s16
	s_add_u32 s10, s4, s15
	s_addc_u32 s11, s5, 0
	global_load_dword v56, v34, s[10:11] nt
	s_add_u32 s10, s10, 0x10000
	s_addc_u32 s11, s11, 0
	global_load_dword v57, v34, s[10:11] nt
	s_add_u32 s10, s10, 0x10000
	s_addc_u32 s11, s11, 0
	global_load_dword v58, v34, s[10:11] nt
	s_add_u32 s10, s10, 0x10000
	s_addc_u32 s11, s11, 0
	global_load_dword v59, v34, s[10:11] nt
	s_add_u32 s10, s10, 0x10000
	s_addc_u32 s11, s11, 0
	global_load_dword v60, v34, s[10:11] nt
	s_add_u32 s10, s10, 0x10000
	s_addc_u32 s11, s11, 0
	global_load_dword v61, v34, s[10:11] nt
	s_add_u32 s10, s10, 0x10000
	s_addc_u32 s11, s11, 0
	global_load_dword v62, v34, s[10:11] nt
	s_add_u32 s10, s10, 0x10000
	s_addc_u32 s11, s11, 0
	global_load_dword v63, v34, s[10:11] nt
	s_mul_i32 s12, s21, 3
	s_add_u32 s12, s12, s8
	s_cmp_ge_u32 s12, 0x200
	s_cbranch_scc1 .Lcv_wbr0_l1_p0_ld_done
	s_mul_i32 s12, s21, 3
	s_add_u32 s12, s12, s8
	s_lshr_b32 s13, s12, 5
	s_and_b32 s14, s12, 31
	s_mul_i32 s15, s13, 0x80000
	s_lshl_b32 s16, s14, 8
	s_add_u32 s15, s15, s16
	s_add_u32 s10, s4, s15
	s_addc_u32 s11, s5, 0
	global_load_dword v64, v34, s[10:11] nt
	s_add_u32 s10, s10, 0x10000
	s_addc_u32 s11, s11, 0
	global_load_dword v65, v34, s[10:11] nt
	s_add_u32 s10, s10, 0x10000
	s_addc_u32 s11, s11, 0
	global_load_dword v66, v34, s[10:11] nt
	s_add_u32 s10, s10, 0x10000
	s_addc_u32 s11, s11, 0
	global_load_dword v67, v34, s[10:11] nt
	s_add_u32 s10, s10, 0x10000
	s_addc_u32 s11, s11, 0
	global_load_dword v68, v34, s[10:11] nt
	s_add_u32 s10, s10, 0x10000
	s_addc_u32 s11, s11, 0
	global_load_dword v69, v34, s[10:11] nt
	s_add_u32 s10, s10, 0x10000
	s_addc_u32 s11, s11, 0
	global_load_dword v70, v34, s[10:11] nt
	s_add_u32 s10, s10, 0x10000
	s_addc_u32 s11, s11, 0
	global_load_dword v71, v34, s[10:11] nt
.Lcv_wbr0_l1_p0_ld_done:
	s_waitcnt vmcnt(0)
	ds_write_b32 v30, v40
	ds_write_b32 v30, v41 offset:2080
	ds_write_b32 v30, v42 offset:4160
	ds_write_b32 v30, v43 offset:6240
	ds_write_b32 v30, v44 offset:8320
	ds_write_b32 v30, v45 offset:10400
	ds_write_b32 v30, v46 offset:12480
	ds_write_b32 v30, v47 offset:14560
	s_mul_i32 s12, s21, 1
	s_add_u32 s12, s12, s8
	s_cmp_ge_u32 s12, 0x200
	s_cbranch_scc1 .Lcv_wbr0_l1_p0_wr_done
	ds_write_b32 v30, v48 offset:16640
	ds_write_b32 v30, v49 offset:18720
	ds_write_b32 v30, v50 offset:20800
	ds_write_b32 v30, v51 offset:22880
	ds_write_b32 v30, v52 offset:24960
	ds_write_b32 v30, v53 offset:27040
	ds_write_b32 v30, v54 offset:29120
	ds_write_b32 v30, v55 offset:31200
	s_mul_i32 s12, s21, 2
	s_add_u32 s12, s12, s8
	s_cmp_ge_u32 s12, 0x200
	s_cbranch_scc1 .Lcv_wbr0_l1_p0_wr_done
	ds_write_b32 v30, v56 offset:33280
	ds_write_b32 v30, v57 offset:35360
	ds_write_b32 v30, v58 offset:37440
	ds_write_b32 v30, v59 offset:39520
	ds_write_b32 v30, v60 offset:41600
	ds_write_b32 v30, v61 offset:43680
	ds_write_b32 v30, v62 offset:45760
	ds_write_b32 v30, v63 offset:47840
	s_mul_i32 s12, s21, 3
	s_add_u32 s12, s12, s8
	s_cmp_ge_u32 s12, 0x200
	s_cbranch_scc1 .Lcv_wbr0_l1_p0_wr_done
	ds_write_b32 v30, v64 offset:49920
	ds_write_b32 v30, v65 offset:52000
	ds_write_b32 v30, v66 offset:54080
	ds_write_b32 v30, v67 offset:56160
	ds_write_b32 v30, v68 offset:58240
	ds_write_b32 v30, v69 offset:60320
	ds_write_b32 v30, v70 offset:62400
	ds_write_b32 v30, v71 offset:64480
; DI unsigned cvtpk(float lo, float hi) { unsigned r; asm volatile("v_cvt_pk_bf16_f32 %0, %1, %2" : "=v"(r) : "v"(lo), "v"(hi)); return r; }
; template <class Map>
; DI void conv_T(bf16_t* __restrict__ dst, const float* __restrict__ src, int K, int ldsrc, int nphys, Map map, const float* __restrict__ kscale, float* tile) {
;     ...
;     const int nn = tid & 63, sc = map(n0 + nn);
; #pragma unroll
;     for (int i = 0; i < 8; ++i) { const int kk = i * 8 + (tid >> 6);
;       float v = sc >= 0 ? __builtin_nontemporal_load(&src[(size_t)(k0 + kk) * ldsrc + sc]) : 0.f;
;       if (kscale) v *= kscale[k0 + kk];
;       tile[kk * 65 + nn] = v; }
;     __syncthreads();
;     const int np = tid >> 3, ks = tid & 7;
;     float v[8];
; #pragma unroll
;     for (int j = 0; j < 8; ++j) v[j] = tile[(ks * 8 + j) * 65 + np];
;     u32x4 w = {cvtpk(v[0], v[1]), cvtpk(v[2], v[3]), cvtpk(v[4], v[5]), cvtpk(v[6], v[7])};
;     *(u32x4*)(dst + (size_t)(n0 + np) * K + k0 + ks * 8) = w;
.Lcv_wbr0_l1_p0_wr_done:
	s_waitcnt lgkmcnt(0)
	s_barrier
	ds_read_b32 v40, v32
	ds_read_b32 v41, v32 offset:260
	ds_read_b32 v42, v32 offset:520
	ds_read_b32 v43, v32 offset:780
	ds_read_b32 v44, v32 offset:1040
	ds_read_b32 v45, v32 offset:1300
	ds_read_b32 v46, v32 offset:1560
	ds_read_b32 v47, v32 offset:1820
	s_mul_i32 s12, s21, 1
	s_add_u32 s12, s12, s8
	s_cmp_ge_u32 s12, 0x200
	s_cbranch_scc1 .Lcv_wbr0_l1_p0_rd_done
	ds_read_b32 v48, v32 offset:16640
	ds_read_b32 v49, v32 offset:16900
	ds_read_b32 v50, v32 offset:17160
	ds_read_b32 v51, v32 offset:17420
	ds_read_b32 v52, v32 offset:17680
	ds_read_b32 v53, v32 offset:17940
	ds_read_b32 v54, v32 offset:18200
	ds_read_b32 v55, v32 offset:18460
	s_mul_i32 s12, s21, 2
	s_add_u32 s12, s12, s8
	s_cmp_ge_u32 s12, 0x200
	s_cbranch_scc1 .Lcv_wbr0_l1_p0_rd_done
	ds_read_b32 v56, v32 offset:33280
	ds_read_b32 v57, v32 offset:33540
	ds_read_b32 v58, v32 offset:33800
	ds_read_b32 v59, v32 offset:34060
	ds_read_b32 v60, v32 offset:34320
	ds_read_b32 v61, v32 offset:34580
	ds_read_b32 v62, v32 offset:34840
	ds_read_b32 v63, v32 offset:35100
	s_mul_i32 s12, s21, 3
	s_add_u32 s12, s12, s8
	s_cmp_ge_u32 s12, 0x200
	s_cbranch_scc1 .Lcv_wbr0_l1_p0_rd_done
	ds_read_b32 v64, v32 offset:49920
	ds_read_b32 v65, v32 offset:50180
	ds_read_b32 v66, v32 offset:50440
	ds_read_b32 v67, v32 offset:50700
	ds_read_b32 v68, v32 offset:50960
	ds_read_b32 v69, v32 offset:51220
	ds_read_b32 v70, v32 offset:51480
	ds_read_b32 v71, v32 offset:51740
.Lcv_wbr0_l1_p0_rd_done:
	s_waitcnt lgkmcnt(0)
	s_mov_b32 s12, s8
	s_lshr_b32 s13, s12, 5
	s_and_b32 s14, s12, 31
	s_mul_i32 s15, s14, 0x20000
	s_lshl_b32 s16, s13, 7
	s_add_u32 s15, s15, s16
	s_add_u32 s10, s6, s15
	s_addc_u32 s11, s7, 0
	v_cvt_pk_bf16_f32 v72, v40, v41
	v_cvt_pk_bf16_f32 v73, v42, v43
	v_cvt_pk_bf16_f32 v74, v44, v45
	v_cvt_pk_bf16_f32 v75, v46, v47
	global_store_dwordx4 v35, v[72:75], s[10:11]
	s_mul_i32 s12, s21, 1
	s_add_u32 s12, s12, s8
	s_cmp_ge_u32 s12, 0x200
	s_cbranch_scc1 .Lcv_wbr0_l1_p0_st_done
	s_mul_i32 s12, s21, 1
	s_add_u32 s12, s12, s8
	s_lshr_b32 s13, s12, 5
	s_and_b32 s14, s12, 31
	s_mul_i32 s15, s14, 0x20000
	s_lshl_b32 s16, s13, 7
	s_add_u32 s15, s15, s16
	s_add_u32 s10, s6, s15
	s_addc_u32 s11, s7, 0
	v_cvt_pk_bf16_f32 v76, v48, v49
	v_cvt_pk_bf16_f32 v77, v50, v51
	v_cvt_pk_bf16_f32 v78, v52, v53
	v_cvt_pk_bf16_f32 v79, v54, v55
	global_store_dwordx4 v35, v[76:79], s[10:11]
	s_mul_i32 s12, s21, 2
	s_add_u32 s12, s12, s8
	s_cmp_ge_u32 s12, 0x200
	s_cbranch_scc1 .Lcv_wbr0_l1_p0_st_done
	s_mul_i32 s12, s21, 2
	s_add_u32 s12, s12, s8
	s_lshr_b32 s13, s12, 5
	s_and_b32 s14, s12, 31
	s_mul_i32 s15, s14, 0x20000
	s_lshl_b32 s16, s13, 7
	s_add_u32 s15, s15, s16
	s_add_u32 s10, s6, s15
	s_addc_u32 s11, s7, 0
	v_cvt_pk_bf16_f32 v80, v56, v57
	v_cvt_pk_bf16_f32 v81, v58, v59
	v_cvt_pk_bf16_f32 v82, v60, v61
	v_cvt_pk_bf16_f32 v83, v62, v63
	global_store_dwordx4 v35, v[80:83], s[10:11]
	s_mul_i32 s12, s21, 3
	s_add_u32 s12, s12, s8
	s_cmp_ge_u32 s12, 0x200
	s_cbranch_scc1 .Lcv_wbr0_l1_p0_st_done
	s_mul_i32 s12, s21, 3
	s_add_u32 s12, s12, s8
	s_lshr_b32 s13, s12, 5
	s_and_b32 s14, s12, 31
	s_mul_i32 s15, s14, 0x20000
	s_lshl_b32 s16, s13, 7
	s_add_u32 s15, s15, s16
	s_add_u32 s10, s6, s15
	s_addc_u32 s11, s7, 0
	v_cvt_pk_bf16_f32 v84, v64, v65
	v_cvt_pk_bf16_f32 v85, v66, v67
	v_cvt_pk_bf16_f32 v86, v68, v69
	v_cvt_pk_bf16_f32 v87, v70, v71
	global_store_dwordx4 v35, v[84:87], s[10:11]
.Lcv_wbr0_l1_p0_st_done:
	s_lshl_b32 s12, s21, 2
	s_add_u32 s8, s8, s12
	s_cmp_ge_u32 s8, 0x200
	s_cbranch_scc1 .Lcv_wbr0_l1_end
	s_mov_b32 s12, s8
	s_lshr_b32 s13, s12, 5
	s_and_b32 s14, s12, 31
	s_mul_i32 s15, s13, 0x80000
	s_lshl_b32 s16, s14, 8
	s_add_u32 s15, s15, s16
	s_add_u32 s10, s4, s15
	s_addc_u32 s11, s5, 0
	global_load_dword v40, v34, s[10:11] nt
	s_add_u32 s10, s10, 0x10000
	s_addc_u32 s11, s11, 0
	global_load_dword v41, v34, s[10:11] nt
	s_add_u32 s10, s10, 0x10000
	s_addc_u32 s11, s11, 0
	global_load_dword v42, v34, s[10:11] nt
	s_add_u32 s10, s10, 0x10000
	s_addc_u32 s11, s11, 0
	global_load_dword v43, v34, s[10:11] nt
	s_add_u32 s10, s10, 0x10000
	s_addc_u32 s11, s11, 0
	global_load_dword v44, v34, s[10:11] nt
	s_add_u32 s10, s10, 0x10000
	s_addc_u32 s11, s11, 0
	global_load_dword v45, v34, s[10:11] nt
	s_add_u32 s10, s10, 0x10000
	s_addc_u32 s11, s11, 0
	global_load_dword v46, v34, s[10:11] nt
	s_add_u32 s10, s10, 0x10000
	s_addc_u32 s11, s11, 0
	global_load_dword v47, v34, s[10:11] nt
	s_mul_i32 s12, s21, 1
	s_add_u32 s12, s12, s8
	s_cmp_ge_u32 s12, 0x200
	s_cbranch_scc1 .Lcv_wbr0_l1_p1_ld_done
	s_mul_i32 s12, s21, 1
	s_add_u32 s12, s12, s8
	s_lshr_b32 s13, s12, 5
	s_and_b32 s14, s12, 31
	s_mul_i32 s15, s13, 0x80000
	s_lshl_b32 s16, s14, 8
	s_add_u32 s15, s15, s16
	s_add_u32 s10, s4, s15
	s_addc_u32 s11, s5, 0
	global_load_dword v48, v34, s[10:11] nt
	s_add_u32 s10, s10, 0x10000
	s_addc_u32 s11, s11, 0
	global_load_dword v49, v34, s[10:11] nt
	s_add_u32 s10, s10, 0x10000
	s_addc_u32 s11, s11, 0
	global_load_dword v50, v34, s[10:11] nt
	s_add_u32 s10, s10, 0x10000
	s_addc_u32 s11, s11, 0
	global_load_dword v51, v34, s[10:11] nt
	s_add_u32 s10, s10, 0x10000
	s_addc_u32 s11, s11, 0
	global_load_dword v52, v34, s[10:11] nt
	s_add_u32 s10, s10, 0x10000
	s_addc_u32 s11, s11, 0
	global_load_dword v53, v34, s[10:11] nt
	s_add_u32 s10, s10, 0x10000
	s_addc_u32 s11, s11, 0
	global_load_dword v54, v34, s[10:11] nt
	s_add_u32 s10, s10, 0x10000
	s_addc_u32 s11, s11, 0
	global_load_dword v55, v34, s[10:11] nt
	s_mul_i32 s12, s21, 2
	s_add_u32 s12, s12, s8
	s_cmp_ge_u32 s12, 0x200
	s_cbranch_scc1 .Lcv_wbr0_l1_p1_ld_done
; template <class Map>
; DI void conv_T(bf16_t* __restrict__ dst, const float* __restrict__ src, int K, int ldsrc, int nphys, Map map, const float* __restrict__ kscale, float* tile) {
;     ...
;     for (int i = 0; i < 8; ++i) { const int kk = i * 8 + (tid >> 6);
;       float v = sc >= 0 ? __builtin_nontemporal_load(&src[(size_t)(k0 + kk) * ldsrc + sc]) : 0.f;
;       if (kscale) v *= kscale[k0 + kk];
;       tile[kk * 65 + nn] = v; }
;     __syncthreads();
;     const int np = tid >> 3, ks = tid & 7;
;     float v[8];
; #pragma unroll
;     for (int j = 0; j < 8; ++j) v[j] = tile[(ks * 8 + j) * 65 + np];
	s_mul_i32 s12, s21, 2
	s_add_u32 s12, s12, s8
	s_lshr_b32 s13, s12, 5
	s_and_b32 s14, s12, 31
	s_mul_i32 s15, s13, 0x80000
	s_lshl_b32 s16, s14, 8
	s_add_u32 s15, s15, s16
	s_add_u32 s10, s4, s15
	s_addc_u32 s11, s5, 0
	global_load_dword v56, v34, s[10:11] nt
	s_add_u32 s10, s10, 0x10000
	s_addc_u32 s11, s11, 0
	global_load_dword v57, v34, s[10:11] nt
	s_add_u32 s10, s10, 0x10000
	s_addc_u32 s11, s11, 0
	global_load_dword v58, v34, s[10:11] nt
	s_add_u32 s10, s10, 0x10000
	s_addc_u32 s11, s11, 0
	global_load_dword v59, v34, s[10:11] nt
	s_add_u32 s10, s10, 0x10000
	s_addc_u32 s11, s11, 0
	global_load_dword v60, v34, s[10:11] nt
	s_add_u32 s10, s10, 0x10000
	s_addc_u32 s11, s11, 0
	global_load_dword v61, v34, s[10:11] nt
	s_add_u32 s10, s10, 0x10000
	s_addc_u32 s11, s11, 0
	global_load_dword v62, v34, s[10:11] nt
	s_add_u32 s10, s10, 0x10000
	s_addc_u32 s11, s11, 0
	global_load_dword v63, v34, s[10:11] nt
	s_mul_i32 s12, s21, 3
	s_add_u32 s12, s12, s8
	s_cmp_ge_u32 s12, 0x200
	s_cbranch_scc1 .Lcv_wbr0_l1_p1_ld_done
	s_mul_i32 s12, s21, 3
	s_add_u32 s12, s12, s8
	s_lshr_b32 s13, s12, 5
	s_and_b32 s14, s12, 31
	s_mul_i32 s15, s13, 0x80000
	s_lshl_b32 s16, s14, 8
	s_add_u32 s15, s15, s16
	s_add_u32 s10, s4, s15
	s_addc_u32 s11, s5, 0
	global_load_dword v64, v34, s[10:11] nt
	s_add_u32 s10, s10, 0x10000
	s_addc_u32 s11, s11, 0
	global_load_dword v65, v34, s[10:11] nt
	s_add_u32 s10, s10, 0x10000
	s_addc_u32 s11, s11, 0
	global_load_dword v66, v34, s[10:11] nt
	s_add_u32 s10, s10, 0x10000
	s_addc_u32 s11, s11, 0
	global_load_dword v67, v34, s[10:11] nt
	s_add_u32 s10, s10, 0x10000
	s_addc_u32 s11, s11, 0
	global_load_dword v68, v34, s[10:11] nt
	s_add_u32 s10, s10, 0x10000
	s_addc_u32 s11, s11, 0
	global_load_dword v69, v34, s[10:11] nt
	s_add_u32 s10, s10, 0x10000
	s_addc_u32 s11, s11, 0
	global_load_dword v70, v34, s[10:11] nt
	s_add_u32 s10, s10, 0x10000
	s_addc_u32 s11, s11, 0
	global_load_dword v71, v34, s[10:11] nt
.Lcv_wbr0_l1_p1_ld_done:
	s_waitcnt vmcnt(0)
	ds_write_b32 v31, v40
	ds_write_b32 v31, v41 offset:2080
	ds_write_b32 v31, v42 offset:4160
	ds_write_b32 v31, v43 offset:6240
	ds_write_b32 v31, v44 offset:8320
	ds_write_b32 v31, v45 offset:10400
	ds_write_b32 v31, v46 offset:12480
	ds_write_b32 v31, v47 offset:14560
	s_mul_i32 s12, s21, 1
	s_add_u32 s12, s12, s8
	s_cmp_ge_u32 s12, 0x200
	s_cbranch_scc1 .Lcv_wbr0_l1_p1_wr_done
	ds_write_b32 v31, v48 offset:16640
	ds_write_b32 v31, v49 offset:18720
	ds_write_b32 v31, v50 offset:20800
	ds_write_b32 v31, v51 offset:22880
	ds_write_b32 v31, v52 offset:24960
	ds_write_b32 v31, v53 offset:27040
	ds_write_b32 v31, v54 offset:29120
	ds_write_b32 v31, v55 offset:31200
	s_mul_i32 s12, s21, 2
	s_add_u32 s12, s12, s8
	s_cmp_ge_u32 s12, 0x200
	s_cbranch_scc1 .Lcv_wbr0_l1_p1_wr_done
	ds_write_b32 v31, v56 offset:33280
	ds_write_b32 v31, v57 offset:35360
	ds_write_b32 v31, v58 offset:37440
	ds_write_b32 v31, v59 offset:39520
	ds_write_b32 v31, v60 offset:41600
	ds_write_b32 v31, v61 offset:43680
	ds_write_b32 v31, v62 offset:45760
	ds_write_b32 v31, v63 offset:47840
	s_mul_i32 s12, s21, 3
	s_add_u32 s12, s12, s8
	s_cmp_ge_u32 s12, 0x200
	s_cbranch_scc1 .Lcv_wbr0_l1_p1_wr_done
	ds_write_b32 v31, v64 offset:49920
	ds_write_b32 v31, v65 offset:52000
	ds_write_b32 v31, v66 offset:54080
	ds_write_b32 v31, v67 offset:56160
	ds_write_b32 v31, v68 offset:58240
	ds_write_b32 v31, v69 offset:60320
	ds_write_b32 v31, v70 offset:62400
	ds_write_b32 v31, v71 offset:64480
.Lcv_wbr0_l1_p1_wr_done:
	s_waitcnt lgkmcnt(0)
	s_barrier
	ds_read_b32 v40, v33
	ds_read_b32 v41, v33 offset:260
	ds_read_b32 v42, v33 offset:520
	ds_read_b32 v43, v33 offset:780
	ds_read_b32 v44, v33 offset:1040
	ds_read_b32 v45, v33 offset:1300
	ds_read_b32 v46, v33 offset:1560
	ds_read_b32 v47, v33 offset:1820
	s_mul_i32 s12, s21, 1
	s_add_u32 s12, s12, s8
	s_cmp_ge_u32 s12, 0x200
	s_cbranch_scc1 .Lcv_wbr0_l1_p1_rd_done
	ds_read_b32 v48, v33 offset:16640
	ds_read_b32 v49, v33 offset:16900
	ds_read_b32 v50, v33 offset:17160
	ds_read_b32 v51, v33 offset:17420
	ds_read_b32 v52, v33 offset:17680
	ds_read_b32 v53, v33 offset:17940
	ds_read_b32 v54, v33 offset:18200
	ds_read_b32 v55, v33 offset:18460
	s_mul_i32 s12, s21, 2
	s_add_u32 s12, s12, s8
	s_cmp_ge_u32 s12, 0x200
	s_cbranch_scc1 .Lcv_wbr0_l1_p1_rd_done
	ds_read_b32 v56, v33 offset:33280
	ds_read_b32 v57, v33 offset:33540
	ds_read_b32 v58, v33 offset:33800
	ds_read_b32 v59, v33 offset:34060
	ds_read_b32 v60, v33 offset:34320
	ds_read_b32 v61, v33 offset:34580
	ds_read_b32 v62, v33 offset:34840
	ds_read_b32 v63, v33 offset:35100
	s_mul_i32 s12, s21, 3
	s_add_u32 s12, s12, s8
	s_cmp_ge_u32 s12, 0x200
	s_cbranch_scc1 .Lcv_wbr0_l1_p1_rd_done
	ds_read_b32 v64, v33 offset:49920
	ds_read_b32 v65, v33 offset:50180
	ds_read_b32 v66, v33 offset:50440
	ds_read_b32 v67, v33 offset:50700
	ds_read_b32 v68, v33 offset:50960
	ds_read_b32 v69, v33 offset:51220
	ds_read_b32 v70, v33 offset:51480
	ds_read_b32 v71, v33 offset:51740

; DI void convert_layer(const Params& p, int l, float* tile) {
;     ...
;   for (int r = 0; r < 3; ++r)
;     conv_T((bf16_t*)(ws + O_WBR) + (size_t)r * 2048 * 1024, p.w_br + (size_t)(l * 3 + r) * 1024 * 2048, 1024, 2048, 2048, MapId{0}, nullptr, tile);
.Lcv_wbr0_l1_p1_st_done:
	s_lshl_b32 s12, s21, 2
	s_add_u32 s8, s8, s12
	s_cmp_ge_u32 s8, 0x200
	s_cbranch_scc0 .Lcv_wbr0_l1_loop
.Lcv_wbr0_l1_end:
	s_waitcnt lgkmcnt(0)
	s_barrier
	v_readlane_b32 s4, v249, 8
	v_readlane_b32 s5, v249, 9
	s_add_u32 s4, s4, 0x2000000
	s_addc_u32 s5, s5, 0
	s_add_u32 s6, s18, 0x4000000
	s_addc_u32 s7, s19, 0
	v_lshrrev_b32_e32 v36, 6, v248
	v_and_b32_e32 v37, 63, v248
	v_mov_b32_e32 v38, 0x2000
	v_mul_u32_u24_e32 v34, v36, v38
	v_lshl_add_u32 v34, v37, 2, v34
	v_lshrrev_b32_e32 v36, 3, v248
	v_and_b32_e32 v37, 7, v248
	v_mov_b32_e32 v38, 0x800
	v_mul_u32_u24_e32 v35, v36, v38
	v_lshl_add_u32 v35, v37, 4, v35
	s_mov_b32 s8, s20
	s_cmp_ge_u32 s8, 0x200
	s_cbranch_scc1 .Lcv_wbr1_l1_end

; DI void convert_layer(const Params& p, int l, float* tile) {
;     ...
;   for (int r = 0; r < 3; ++r)
;     conv_T((bf16_t*)(ws + O_WBR) + (size_t)r * 2048 * 1024, p.w_br + (size_t)(l * 3 + r) * 1024 * 2048, 1024, 2048, 2048, MapId{0}, nullptr, tile);
.Lcv_wbr1_l1_end:
	s_waitcnt lgkmcnt(0)
	s_barrier
	v_readlane_b32 s4, v249, 8
	v_readlane_b32 s5, v249, 9
	s_add_u32 s4, s4, 0x2800000
	s_addc_u32 s5, s5, 0
	s_add_u32 s6, s18, 0x4400000
	s_addc_u32 s7, s19, 0
	v_lshrrev_b32_e32 v36, 6, v248
	v_and_b32_e32 v37, 63, v248
	v_mov_b32_e32 v38, 0x2000
	v_mul_u32_u24_e32 v34, v36, v38
	v_lshl_add_u32 v34, v37, 2, v34
	v_lshrrev_b32_e32 v36, 3, v248
	v_and_b32_e32 v37, 7, v248
	v_mov_b32_e32 v38, 0x800
	v_mul_u32_u24_e32 v35, v36, v38
	v_lshl_add_u32 v35, v37, 4, v35
	s_mov_b32 s8, s20
	s_cmp_ge_u32 s8, 0x200
	s_cbranch_scc1 .Lcv_wbr2_l1_end

; DI int ltid() { int t = threadIdx.x; asm volatile("" : "+v"(t)); return t; }
; DI int lbid() { int b = blockIdx.x; asm volatile("" : "+s"(b)); return b; }
; template <class Map>
; DI void conv_T(bf16_t* __restrict__ dst, const float* __restrict__ src, int K, int ldsrc, int nphys, Map map, const float* __restrict__ kscale, float* tile) {
;   const int tid = ltid(), ntn = nphys >> 6, ntiles = (K >> 6) * ntn;
;   for (int tl = lbid(); tl < ntiles; tl += gridDim.x) {
;     const int k0 = (tl / ntn) << 6, n0 = (tl % ntn) << 6;
;     const int nn = tid & 63, sc = map(n0 + nn);
; #pragma unroll
;     for (int i = 0; i < 8; ++i) { const int kk = i * 8 + (tid >> 6);
;       float v = sc >= 0 ? __builtin_nontemporal_load(&src[(size_t)(k0 + kk) * ldsrc + sc]) : 0.f;
;       if (kscale) v *= kscale[k0 + kk];
;       tile[kk * 65 + nn] = v; }
; DI void convert_layer(const Params& p, int l, float* tile) {
;     ...
;   conv_T((bf16_t*)(ws + O_WO), p.w_o + (size_t)l * 2048 * 2048, 2048, 2048, 2048, MapId{0}, nullptr, tile);
.Lcv_wbr2_l1_end:
	s_waitcnt lgkmcnt(0)
	s_barrier
	v_readlane_b32 s4, v249, 10
	v_readlane_b32 s5, v249, 11
	s_add_u32 s4, s4, 0x1000000
	s_addc_u32 s5, s5, 0
	s_add_u32 s6, s18, 0x4800000
	s_addc_u32 s7, s19, 0
	v_lshrrev_b32_e32 v36, 6, v248
	v_and_b32_e32 v37, 63, v248
	v_mov_b32_e32 v38, 0x2000
	v_mul_u32_u24_e32 v34, v36, v38
	v_lshl_add_u32 v34, v37, 2, v34
	v_lshrrev_b32_e32 v36, 3, v248
	v_and_b32_e32 v37, 7, v248
	v_mov_b32_e32 v38, 0x1000
	v_mul_u32_u24_e32 v35, v36, v38
	v_lshl_add_u32 v35, v37, 4, v35
	s_mov_b32 s8, s20
	s_cmp_ge_u32 s8, 0x400
	s_cbranch_scc1 .Lcv_wo_l1_end
.Lcv_wo_l1_loop:
	s_mov_b32 s12, s8
	s_lshr_b32 s13, s12, 5
	s_and_b32 s14, s12, 31
	s_mul_i32 s15, s13, 0x80000
	s_lshl_b32 s16, s14, 8
	s_add_u32 s15, s15, s16
	s_add_u32 s10, s4, s15
	s_addc_u32 s11, s5, 0
	global_load_dword v40, v34, s[10:11] nt
	s_add_u32 s10, s10, 0x10000
	s_addc_u32 s11, s11, 0
	global_load_dword v41, v34, s[10:11] nt
	s_add_u32 s10, s10, 0x10000
	s_addc_u32 s11, s11, 0
	global_load_dword v42, v34, s[10:11] nt
	s_add_u32 s10, s10, 0x10000
	s_addc_u32 s11, s11, 0
	global_load_dword v43, v34, s[10:11] nt
	s_add_u32 s10, s10, 0x10000
	s_addc_u32 s11, s11, 0
	global_load_dword v44, v34, s[10:11] nt
	s_add_u32 s10, s10, 0x10000
	s_addc_u32 s11, s11, 0
	global_load_dword v45, v34, s[10:11] nt
	s_add_u32 s10, s10, 0x10000
	s_addc_u32 s11, s11, 0
	global_load_dword v46, v34, s[10:11] nt
	s_add_u32 s10, s10, 0x10000
	s_addc_u32 s11, s11, 0
	global_load_dword v47, v34, s[10:11] nt
	s_mul_i32 s12, s21, 1
	s_add_u32 s12, s12, s8
	s_cmp_ge_u32 s12, 0x400
	s_cbranch_scc1 .Lcv_wo_l1_p0_ld_done
	s_mul_i32 s12, s21, 1
	s_add_u32 s12, s12, s8
	s_lshr_b32 s13, s12, 5
	s_and_b32 s14, s12, 31
	s_mul_i32 s15, s13, 0x80000
	s_lshl_b32 s16, s14, 8
	s_add_u32 s15, s15, s16
	s_add_u32 s10, s4, s15
	s_addc_u32 s11, s5, 0
	global_load_dword v48, v34, s[10:11] nt
	s_add_u32 s10, s10, 0x10000
	s_addc_u32 s11, s11, 0
	global_load_dword v49, v34, s[10:11] nt
	s_add_u32 s10, s10, 0x10000
	s_addc_u32 s11, s11, 0
	global_load_dword v50, v34, s[10:11] nt
	s_add_u32 s10, s10, 0x10000
	s_addc_u32 s11, s11, 0
	global_load_dword v51, v34, s[10:11] nt
	s_add_u32 s10, s10, 0x10000
	s_addc_u32 s11, s11, 0
	global_load_dword v52, v34, s[10:11] nt
	s_add_u32 s10, s10, 0x10000
	s_addc_u32 s11, s11, 0
	global_load_dword v53, v34, s[10:11] nt
	s_add_u32 s10, s10, 0x10000
	s_addc_u32 s11, s11, 0
	global_load_dword v54, v34, s[10:11] nt
	s_add_u32 s10, s10, 0x10000
	s_addc_u32 s11, s11, 0
	global_load_dword v55, v34, s[10:11] nt
	s_mul_i32 s12, s21, 2
	s_add_u32 s12, s12, s8
	s_cmp_ge_u32 s12, 0x400
	s_cbranch_scc1 .Lcv_wo_l1_p0_ld_done
	s_mul_i32 s12, s21, 2
	s_add_u32 s12, s12, s8
	s_lshr_b32 s13, s12, 5
	s_and_b32 s14, s12, 31
	s_mul_i32 s15, s13, 0x80000
	s_lshl_b32 s16, s14, 8
	s_add_u32 s15, s15, s16
	s_add_u32 s10, s4, s15
	s_addc_u32 s11, s5, 0
	global_load_dword v56, v34, s[10:11] nt
	s_add_u32 s10, s10, 0x10000
	s_addc_u32 s11, s11, 0
	global_load_dword v57, v34, s[10:11] nt
	s_add_u32 s10, s10, 0x10000
	s_addc_u32 s11, s11, 0
	global_load_dword v58, v34, s[10:11] nt
	s_add_u32 s10, s10, 0x10000
	s_addc_u32 s11, s11, 0
	global_load_dword v59, v34, s[10:11] nt
	s_add_u32 s10, s10, 0x10000
	s_addc_u32 s11, s11, 0
	global_load_dword v60, v34, s[10:11] nt
	s_add_u32 s10, s10, 0x10000
	s_addc_u32 s11, s11, 0
	global_load_dword v61, v34, s[10:11] nt
	s_add_u32 s10, s10, 0x10000
	s_addc_u32 s11, s11, 0
	global_load_dword v62, v34, s[10:11] nt
	s_add_u32 s10, s10, 0x10000
	s_addc_u32 s11, s11, 0
	global_load_dword v63, v34, s[10:11] nt
	s_mul_i32 s12, s21, 3
	s_add_u32 s12, s12, s8
	s_cmp_ge_u32 s12, 0x400
	s_cbranch_scc1 .Lcv_wo_l1_p0_ld_done
	s_mul_i32 s12, s21, 3
	s_add_u32 s12, s12, s8
	s_lshr_b32 s13, s12, 5
	s_and_b32 s14, s12, 31
	s_mul_i32 s15, s13, 0x80000
	s_lshl_b32 s16, s14, 8
	s_add_u32 s15, s15, s16
	s_add_u32 s10, s4, s15
	s_addc_u32 s11, s5, 0
	global_load_dword v64, v34, s[10:11] nt
	s_add_u32 s10, s10, 0x10000
	s_addc_u32 s11, s11, 0
	global_load_dword v65, v34, s[10:11] nt
	s_add_u32 s10, s10, 0x10000
	s_addc_u32 s11, s11, 0
	global_load_dword v66, v34, s[10:11] nt
	s_add_u32 s10, s10, 0x10000
	s_addc_u32 s11, s11, 0
	global_load_dword v67, v34, s[10:11] nt
	s_add_u32 s10, s10, 0x10000
	s_addc_u32 s11, s11, 0
	global_load_dword v68, v34, s[10:11] nt
	s_add_u32 s10, s10, 0x10000
	s_addc_u32 s11, s11, 0
	global_load_dword v69, v34, s[10:11] nt
	s_add_u32 s10, s10, 0x10000
	s_addc_u32 s11, s11, 0
	global_load_dword v70, v34, s[10:11] nt
	s_add_u32 s10, s10, 0x10000
	s_addc_u32 s11, s11, 0
	global_load_dword v71, v34, s[10:11] nt
.Lcv_wo_l1_p0_ld_done:
	s_waitcnt vmcnt(0)
	ds_write_b32 v30, v40
	ds_write_b32 v30, v41 offset:2080
	ds_write_b32 v30, v42 offset:4160
	ds_write_b32 v30, v43 offset:6240
	ds_write_b32 v30, v44 offset:8320
	ds_write_b32 v30, v45 offset:10400
	ds_write_b32 v30, v46 offset:12480
	ds_write_b32 v30, v47 offset:14560
	s_mul_i32 s12, s21, 1
	s_add_u32 s12, s12, s8
	s_cmp_ge_u32 s12, 0x400
	s_cbranch_scc1 .Lcv_wo_l1_p0_wr_done
	ds_write_b32 v30, v48 offset:16640
	ds_write_b32 v30, v49 offset:18720
	ds_write_b32 v30, v50 offset:20800
	ds_write_b32 v30, v51 offset:22880
	ds_write_b32 v30, v52 offset:24960
	ds_write_b32 v30, v53 offset:27040
	ds_write_b32 v30, v54 offset:29120
	ds_write_b32 v30, v55 offset:31200
	s_mul_i32 s12, s21, 2
	s_add_u32 s12, s12, s8
	s_cmp_ge_u32 s12, 0x400
	s_cbranch_scc1 .Lcv_wo_l1_p0_wr_done
	ds_write_b32 v30, v56 offset:33280
	ds_write_b32 v30, v57 offset:35360
	ds_write_b32 v30, v58 offset:37440
	ds_write_b32 v30, v59 offset:39520
	ds_write_b32 v30, v60 offset:41600
	ds_write_b32 v30, v61 offset:43680
	ds_write_b32 v30, v62 offset:45760
	ds_write_b32 v30, v63 offset:47840
	s_mul_i32 s12, s21, 3
	s_add_u32 s12, s12, s8
	s_cmp_ge_u32 s12, 0x400
	s_cbranch_scc1 .Lcv_wo_l1_p0_wr_done
	ds_write_b32 v30, v64 offset:49920
	ds_write_b32 v30, v65 offset:52000
	ds_write_b32 v30, v66 offset:54080
	ds_write_b32 v30, v67 offset:56160
	ds_write_b32 v30, v68 offset:58240
	ds_write_b32 v30, v69 offset:60320
	ds_write_b32 v30, v70 offset:62400
	ds_write_b32 v30, v71 offset:64480
; DI unsigned cvtpk(float lo, float hi) { unsigned r; asm volatile("v_cvt_pk_bf16_f32 %0, %1, %2" : "=v"(r) : "v"(lo), "v"(hi)); return r; }
; template <class Map>
; DI void conv_T(bf16_t* __restrict__ dst, const float* __restrict__ src, int K, int ldsrc, int nphys, Map map, const float* __restrict__ kscale, float* tile) {
;     ...
;     const int nn = tid & 63, sc = map(n0 + nn);
; #pragma unroll
;     for (int i = 0; i < 8; ++i) { const int kk = i * 8 + (tid >> 6);
;       float v = sc >= 0 ? __builtin_nontemporal_load(&src[(size_t)(k0 + kk) * ldsrc + sc]) : 0.f;
;       if (kscale) v *= kscale[k0 + kk];
;       tile[kk * 65 + nn] = v; }
;     __syncthreads();
;     const int np = tid >> 3, ks = tid & 7;
;     float v[8];
; #pragma unroll
;     for (int j = 0; j < 8; ++j) v[j] = tile[(ks * 8 + j) * 65 + np];
;     u32x4 w = {cvtpk(v[0], v[1]), cvtpk(v[2], v[3]), cvtpk(v[4], v[5]), cvtpk(v[6], v[7])};
;     *(u32x4*)(dst + (size_t)(n0 + np) * K + k0 + ks * 8) = w;
.Lcv_wo_l1_p0_wr_done:
	s_waitcnt lgkmcnt(0)
	s_barrier
	ds_read_b32 v40, v32
	ds_read_b32 v41, v32 offset:260
	ds_read_b32 v42, v32 offset:520
	ds_read_b32 v43, v32 offset:780
	ds_read_b32 v44, v32 offset:1040
	ds_read_b32 v45, v32 offset:1300
	ds_read_b32 v46, v32 offset:1560
	ds_read_b32 v47, v32 offset:1820
	s_mul_i32 s12, s21, 1
	s_add_u32 s12, s12, s8
	s_cmp_ge_u32 s12, 0x400
	s_cbranch_scc1 .Lcv_wo_l1_p0_rd_done
	ds_read_b32 v48, v32 offset:16640
	ds_read_b32 v49, v32 offset:16900
	ds_read_b32 v50, v32 offset:17160
	ds_read_b32 v51, v32 offset:17420
	ds_read_b32 v52, v32 offset:17680
	ds_read_b32 v53, v32 offset:17940
	ds_read_b32 v54, v32 offset:18200
	ds_read_b32 v55, v32 offset:18460
	s_mul_i32 s12, s21, 2
	s_add_u32 s12, s12, s8
	s_cmp_ge_u32 s12, 0x400
	s_cbranch_scc1 .Lcv_wo_l1_p0_rd_done
	ds_read_b32 v56, v32 offset:33280
	ds_read_b32 v57, v32 offset:33540
	ds_read_b32 v58, v32 offset:33800
	ds_read_b32 v59, v32 offset:34060
	ds_read_b32 v60, v32 offset:34320
	ds_read_b32 v61, v32 offset:34580
	ds_read_b32 v62, v32 offset:34840
	ds_read_b32 v63, v32 offset:35100
	s_mul_i32 s12, s21, 3
	s_add_u32 s12, s12, s8
	s_cmp_ge_u32 s12, 0x400
	s_cbranch_scc1 .Lcv_wo_l1_p0_rd_done
	ds_read_b32 v64, v32 offset:49920
	ds_read_b32 v65, v32 offset:50180
	ds_read_b32 v66, v32 offset:50440
	ds_read_b32 v67, v32 offset:50700
	ds_read_b32 v68, v32 offset:50960
	ds_read_b32 v69, v32 offset:51220
	ds_read_b32 v70, v32 offset:51480
	ds_read_b32 v71, v32 offset:51740
.Lcv_wo_l1_p0_rd_done:
	s_waitcnt lgkmcnt(0)
	s_mov_b32 s12, s8
	s_lshr_b32 s13, s12, 5
	s_and_b32 s14, s12, 31
	s_mul_i32 s15, s14, 0x40000
	s_lshl_b32 s16, s13, 7
	s_add_u32 s15, s15, s16
	s_add_u32 s10, s6, s15
	s_addc_u32 s11, s7, 0
	v_cvt_pk_bf16_f32 v72, v40, v41
	v_cvt_pk_bf16_f32 v73, v42, v43
	v_cvt_pk_bf16_f32 v74, v44, v45
	v_cvt_pk_bf16_f32 v75, v46, v47
	global_store_dwordx4 v35, v[72:75], s[10:11]
	s_mul_i32 s12, s21, 1
	s_add_u32 s12, s12, s8
	s_cmp_ge_u32 s12, 0x400
	s_cbranch_scc1 .Lcv_wo_l1_p0_st_done
	s_mul_i32 s12, s21, 1
	s_add_u32 s12, s12, s8
	s_lshr_b32 s13, s12, 5
	s_and_b32 s14, s12, 31
	s_mul_i32 s15, s14, 0x40000
	s_lshl_b32 s16, s13, 7
	s_add_u32 s15, s15, s16
	s_add_u32 s10, s6, s15
	s_addc_u32 s11, s7, 0
	v_cvt_pk_bf16_f32 v76, v48, v49
	v_cvt_pk_bf16_f32 v77, v50, v51
	v_cvt_pk_bf16_f32 v78, v52, v53
	v_cvt_pk_bf16_f32 v79, v54, v55
	global_store_dwordx4 v35, v[76:79], s[10:11]
	s_mul_i32 s12, s21, 2
	s_add_u32 s12, s12, s8
	s_cmp_ge_u32 s12, 0x400
	s_cbranch_scc1 .Lcv_wo_l1_p0_st_done
	s_mul_i32 s12, s21, 2
	s_add_u32 s12, s12, s8
	s_lshr_b32 s13, s12, 5
	s_and_b32 s14, s12, 31
	s_mul_i32 s15, s14, 0x40000
	s_lshl_b32 s16, s13, 7
	s_add_u32 s15, s15, s16
	s_add_u32 s10, s6, s15
	s_addc_u32 s11, s7, 0
	v_cvt_pk_bf16_f32 v80, v56, v57
	v_cvt_pk_bf16_f32 v81, v58, v59
	v_cvt_pk_bf16_f32 v82, v60, v61
	v_cvt_pk_bf16_f32 v83, v62, v63
	global_store_dwordx4 v35, v[80:83], s[10:11]
	s_mul_i32 s12, s21, 3
	s_add_u32 s12, s12, s8
	s_cmp_ge_u32 s12, 0x400
	s_cbranch_scc1 .Lcv_wo_l1_p0_st_done
	s_mul_i32 s12, s21, 3
	s_add_u32 s12, s12, s8
	s_lshr_b32 s13, s12, 5
	s_and_b32 s14, s12, 31
	s_mul_i32 s15, s14, 0x40000
	s_lshl_b32 s16, s13, 7
	s_add_u32 s15, s15, s16
	s_add_u32 s10, s6, s15
	s_addc_u32 s11, s7, 0
	v_cvt_pk_bf16_f32 v84, v64, v65
	v_cvt_pk_bf16_f32 v85, v66, v67
	v_cvt_pk_bf16_f32 v86, v68, v69
	v_cvt_pk_bf16_f32 v87, v70, v71
	global_store_dwordx4 v35, v[84:87], s[10:11]
.Lcv_wo_l1_p0_st_done:
	s_lshl_b32 s12, s21, 2
	s_add_u32 s8, s8, s12
	s_cmp_ge_u32 s8, 0x400
	s_cbranch_scc1 .Lcv_wo_l1_end
	s_mov_b32 s12, s8
	s_lshr_b32 s13, s12, 5
	s_and_b32 s14, s12, 31
	s_mul_i32 s15, s13, 0x80000
	s_lshl_b32 s16, s14, 8
	s_add_u32 s15, s15, s16
	s_add_u32 s10, s4, s15
	s_addc_u32 s11, s5, 0
	global_load_dword v40, v34, s[10:11] nt
	s_add_u32 s10, s10, 0x10000
	s_addc_u32 s11, s11, 0
	global_load_dword v41, v34, s[10:11] nt
	s_add_u32 s10, s10, 0x10000
	s_addc_u32 s11, s11, 0
	global_load_dword v42, v34, s[10:11] nt
	s_add_u32 s10, s10, 0x10000
	s_addc_u32 s11, s11, 0
	global_load_dword v43, v34, s[10:11] nt
	s_add_u32 s10, s10, 0x10000
	s_addc_u32 s11, s11, 0
	global_load_dword v44, v34, s[10:11] nt
	s_add_u32 s10, s10, 0x10000
	s_addc_u32 s11, s11, 0
	global_load_dword v45, v34, s[10:11] nt
	s_add_u32 s10, s10, 0x10000
	s_addc_u32 s11, s11, 0
	global_load_dword v46, v34, s[10:11] nt
	s_add_u32 s10, s10, 0x10000
	s_addc_u32 s11, s11, 0
	global_load_dword v47, v34, s[10:11] nt
	s_mul_i32 s12, s21, 1
	s_add_u32 s12, s12, s8
	s_cmp_ge_u32 s12, 0x400
	s_cbranch_scc1 .Lcv_wo_l1_p1_ld_done
	s_mul_i32 s12, s21, 1
	s_add_u32 s12, s12, s8
	s_lshr_b32 s13, s12, 5
	s_and_b32 s14, s12, 31
	s_mul_i32 s15, s13, 0x80000
	s_lshl_b32 s16, s14, 8
	s_add_u32 s15, s15, s16
	s_add_u32 s10, s4, s15
	s_addc_u32 s11, s5, 0
	global_load_dword v48, v34, s[10:11] nt
	s_add_u32 s10, s10, 0x10000
	s_addc_u32 s11, s11, 0
	global_load_dword v49, v34, s[10:11] nt
	s_add_u32 s10, s10, 0x10000
	s_addc_u32 s11, s11, 0
	global_load_dword v50, v34, s[10:11] nt
	s_add_u32 s10, s10, 0x10000
	s_addc_u32 s11, s11, 0
	global_load_dword v51, v34, s[10:11] nt
	s_add_u32 s10, s10, 0x10000
	s_addc_u32 s11, s11, 0
	global_load_dword v52, v34, s[10:11] nt
	s_add_u32 s10, s10, 0x10000
	s_addc_u32 s11, s11, 0
	global_load_dword v53, v34, s[10:11] nt
	s_add_u32 s10, s10, 0x10000
	s_addc_u32 s11, s11, 0
	global_load_dword v54, v34, s[10:11] nt
	s_add_u32 s10, s10, 0x10000
	s_addc_u32 s11, s11, 0
	global_load_dword v55, v34, s[10:11] nt
	s_mul_i32 s12, s21, 2
	s_add_u32 s12, s12, s8
	s_cmp_ge_u32 s12, 0x400
	s_cbranch_scc1 .Lcv_wo_l1_p1_ld_done
; template <class Map>
; DI void conv_T(bf16_t* __restrict__ dst, const float* __restrict__ src, int K, int ldsrc, int nphys, Map map, const float* __restrict__ kscale, float* tile) {
;     ...
;     for (int i = 0; i < 8; ++i) { const int kk = i * 8 + (tid >> 6);
;       float v = sc >= 0 ? __builtin_nontemporal_load(&src[(size_t)(k0 + kk) * ldsrc + sc]) : 0.f;
;       if (kscale) v *= kscale[k0 + kk];
;       tile[kk * 65 + nn] = v; }
;     __syncthreads();
;     const int np = tid >> 3, ks = tid & 7;
;     float v[8];
; #pragma unroll
;     for (int j = 0; j < 8; ++j) v[j] = tile[(ks * 8 + j) * 65 + np];
	s_mul_i32 s12, s21, 2
	s_add_u32 s12, s12, s8
	s_lshr_b32 s13, s12, 5
	s_and_b32 s14, s12, 31
	s_mul_i32 s15, s13, 0x80000
	s_lshl_b32 s16, s14, 8
	s_add_u32 s15, s15, s16
	s_add_u32 s10, s4, s15
	s_addc_u32 s11, s5, 0
	global_load_dword v56, v34, s[10:11] nt
	s_add_u32 s10, s10, 0x10000
	s_addc_u32 s11, s11, 0
	global_load_dword v57, v34, s[10:11] nt
	s_add_u32 s10, s10, 0x10000
	s_addc_u32 s11, s11, 0
	global_load_dword v58, v34, s[10:11] nt
	s_add_u32 s10, s10, 0x10000
	s_addc_u32 s11, s11, 0
	global_load_dword v59, v34, s[10:11] nt
	s_add_u32 s10, s10, 0x10000
	s_addc_u32 s11, s11, 0
	global_load_dword v60, v34, s[10:11] nt
	s_add_u32 s10, s10, 0x10000
	s_addc_u32 s11, s11, 0
	global_load_dword v61, v34, s[10:11] nt
	s_add_u32 s10, s10, 0x10000
	s_addc_u32 s11, s11, 0
	global_load_dword v62, v34, s[10:11] nt
	s_add_u32 s10, s10, 0x10000
	s_addc_u32 s11, s11, 0
	global_load_dword v63, v34, s[10:11] nt
	s_mul_i32 s12, s21, 3
	s_add_u32 s12, s12, s8
	s_cmp_ge_u32 s12, 0x400
	s_cbranch_scc1 .Lcv_wo_l1_p1_ld_done
	s_mul_i32 s12, s21, 3
	s_add_u32 s12, s12, s8
	s_lshr_b32 s13, s12, 5
	s_and_b32 s14, s12, 31
	s_mul_i32 s15, s13, 0x80000
	s_lshl_b32 s16, s14, 8
	s_add_u32 s15, s15, s16
	s_add_u32 s10, s4, s15
	s_addc_u32 s11, s5, 0
	global_load_dword v64, v34, s[10:11] nt
	s_add_u32 s10, s10, 0x10000
	s_addc_u32 s11, s11, 0
	global_load_dword v65, v34, s[10:11] nt
	s_add_u32 s10, s10, 0x10000
	s_addc_u32 s11, s11, 0
	global_load_dword v66, v34, s[10:11] nt
	s_add_u32 s10, s10, 0x10000
	s_addc_u32 s11, s11, 0
	global_load_dword v67, v34, s[10:11] nt
	s_add_u32 s10, s10, 0x10000
	s_addc_u32 s11, s11, 0
	global_load_dword v68, v34, s[10:11] nt
	s_add_u32 s10, s10, 0x10000
	s_addc_u32 s11, s11, 0
	global_load_dword v69, v34, s[10:11] nt
	s_add_u32 s10, s10, 0x10000
	s_addc_u32 s11, s11, 0
	global_load_dword v70, v34, s[10:11] nt
	s_add_u32 s10, s10, 0x10000
	s_addc_u32 s11, s11, 0
	global_load_dword v71, v34, s[10:11] nt
.Lcv_wo_l1_p1_ld_done:
	s_waitcnt vmcnt(0)
	ds_write_b32 v31, v40
	ds_write_b32 v31, v41 offset:2080
	ds_write_b32 v31, v42 offset:4160
	ds_write_b32 v31, v43 offset:6240
	ds_write_b32 v31, v44 offset:8320
	ds_write_b32 v31, v45 offset:10400
	ds_write_b32 v31, v46 offset:12480
	ds_write_b32 v31, v47 offset:14560
	s_mul_i32 s12, s21, 1
	s_add_u32 s12, s12, s8
	s_cmp_ge_u32 s12, 0x400
	s_cbranch_scc1 .Lcv_wo_l1_p1_wr_done
	ds_write_b32 v31, v48 offset:16640
	ds_write_b32 v31, v49 offset:18720
	ds_write_b32 v31, v50 offset:20800
	ds_write_b32 v31, v51 offset:22880
	ds_write_b32 v31, v52 offset:24960
	ds_write_b32 v31, v53 offset:27040
	ds_write_b32 v31, v54 offset:29120
	ds_write_b32 v31, v55 offset:31200
	s_mul_i32 s12, s21, 2
	s_add_u32 s12, s12, s8
	s_cmp_ge_u32 s12, 0x400
	s_cbranch_scc1 .Lcv_wo_l1_p1_wr_done
	ds_write_b32 v31, v56 offset:33280
	ds_write_b32 v31, v57 offset:35360
	ds_write_b32 v31, v58 offset:37440
	ds_write_b32 v31, v59 offset:39520
	ds_write_b32 v31, v60 offset:41600
	ds_write_b32 v31, v61 offset:43680
	ds_write_b32 v31, v62 offset:45760
	ds_write_b32 v31, v63 offset:47840
	s_mul_i32 s12, s21, 3
	s_add_u32 s12, s12, s8
	s_cmp_ge_u32 s12, 0x400
	s_cbranch_scc1 .Lcv_wo_l1_p1_wr_done
	ds_write_b32 v31, v64 offset:49920
	ds_write_b32 v31, v65 offset:52000
	ds_write_b32 v31, v66 offset:54080
	ds_write_b32 v31, v67 offset:56160
	ds_write_b32 v31, v68 offset:58240
	ds_write_b32 v31, v69 offset:60320
	ds_write_b32 v31, v70 offset:62400
	ds_write_b32 v31, v71 offset:64480
.Lcv_wo_l1_p1_wr_done:
	s_waitcnt lgkmcnt(0)
	s_barrier
	ds_read_b32 v40, v33
	ds_read_b32 v41, v33 offset:260
	ds_read_b32 v42, v33 offset:520
	ds_read_b32 v43, v33 offset:780
	ds_read_b32 v44, v33 offset:1040
	ds_read_b32 v45, v33 offset:1300
	ds_read_b32 v46, v33 offset:1560
	ds_read_b32 v47, v33 offset:1820
	s_mul_i32 s12, s21, 1
	s_add_u32 s12, s12, s8
	s_cmp_ge_u32 s12, 0x400
	s_cbranch_scc1 .Lcv_wo_l1_p1_rd_done
	ds_read_b32 v48, v33 offset:16640
	ds_read_b32 v49, v33 offset:16900
	ds_read_b32 v50, v33 offset:17160
	ds_read_b32 v51, v33 offset:17420
	ds_read_b32 v52, v33 offset:17680
	ds_read_b32 v53, v33 offset:17940
	ds_read_b32 v54, v33 offset:18200
	ds_read_b32 v55, v33 offset:18460
	s_mul_i32 s12, s21, 2
	s_add_u32 s12, s12, s8
	s_cmp_ge_u32 s12, 0x400
	s_cbranch_scc1 .Lcv_wo_l1_p1_rd_done
	ds_read_b32 v56, v33 offset:33280
	ds_read_b32 v57, v33 offset:33540
	ds_read_b32 v58, v33 offset:33800
	ds_read_b32 v59, v33 offset:34060
	ds_read_b32 v60, v33 offset:34320
	ds_read_b32 v61, v33 offset:34580
	ds_read_b32 v62, v33 offset:34840
	ds_read_b32 v63, v33 offset:35100
	s_mul_i32 s12, s21, 3
	s_add_u32 s12, s12, s8
	s_cmp_ge_u32 s12, 0x400
	s_cbranch_scc1 .Lcv_wo_l1_p1_rd_done
	ds_read_b32 v64, v33 offset:49920
	ds_read_b32 v65, v33 offset:50180
	ds_read_b32 v66, v33 offset:50440
	ds_read_b32 v67, v33 offset:50700
	ds_read_b32 v68, v33 offset:50960
	ds_read_b32 v69, v33 offset:51220
	ds_read_b32 v70, v33 offset:51480
	ds_read_b32 v71, v33 offset:51740

; DI int ltid() { int t = threadIdx.x; asm volatile("" : "+v"(t)); return t; }
; DI int lbid() { int b = blockIdx.x; asm volatile("" : "+s"(b)); return b; }
; template <class Map>
; DI void conv_T(bf16_t* __restrict__ dst, const float* __restrict__ src, int K, int ldsrc, int nphys, Map map, const float* __restrict__ kscale, float* tile) {
;   const int tid = ltid(), ntn = nphys >> 6, ntiles = (K >> 6) * ntn;
;   for (int tl = lbid(); tl < ntiles; tl += gridDim.x) {
;     const int k0 = (tl / ntn) << 6, n0 = (tl % ntn) << 6;
;     const int nn = tid & 63, sc = map(n0 + nn);
; #pragma unroll
;     for (int i = 0; i < 8; ++i) { const int kk = i * 8 + (tid >> 6);
;       float v = sc >= 0 ? __builtin_nontemporal_load(&src[(size_t)(k0 + kk) * ldsrc + sc]) : 0.f;
;       if (kscale) v *= kscale[k0 + kk];
;       tile[kk * 65 + nn] = v; }
; DI void convert_layer(const Params& p, int l, float* tile) {
;     ...
;   conv_T((bf16_t*)(ws + O_WF1), p.w_f1 + (size_t)l * 2048 * 2 * DFF, 2048, 2 * DFF, 2 * DFF, MapF1{}, nullptr, tile);
.Lcv_wo_l1_p1_st_done:
	s_lshl_b32 s12, s21, 2
	s_add_u32 s8, s8, s12
	s_cmp_ge_u32 s8, 0x400
	s_cbranch_scc0 .Lcv_wo_l1_loop
.Lcv_wo_l1_end:
	s_waitcnt lgkmcnt(0)
	s_barrier
	v_readlane_b32 s4, v249, 12
	v_readlane_b32 s5, v249, 13
	s_add_u32 s4, s4, 0x5800000
	s_addc_u32 s5, s5, 0
	s_add_u32 s6, s18, 0x5000000
	s_addc_u32 s7, s19, 0
	v_lshrrev_b32_e32 v36, 6, v248
	v_and_b32_e32 v37, 63, v248
	v_mov_b32_e32 v38, 0xb000
	v_mul_u32_u24_e32 v34, v36, v38
	v_lshrrev_b32_e32 v36, 5, v37
	v_and_b32_e32 v38, 31, v37
	v_lshl_add_u32 v36, v36, 4, v38
	v_and_b32_e32 v38, 16, v37
	v_mul_u32_u24_e32 v38, 0x15f, v38
	v_add_u32_e32 v37, v36, v38
	v_lshl_add_u32 v34, v37, 2, v34
	v_lshrrev_b32_e32 v36, 3, v248
	v_and_b32_e32 v37, 7, v248
	v_mov_b32_e32 v38, 0x1000
	v_mul_u32_u24_e32 v35, v36, v38
	v_lshl_add_u32 v35, v37, 4, v35
	s_mov_b32 s8, s20
	s_cmp_ge_u32 s8, 0x1600
	s_cbranch_scc1 .Lcv_wf1_l1_end
.Lcv_wf1_l1_loop:
	s_mov_b32 s12, s8
	s_mul_i32 s13, s12, 0xba3
	s_lshr_b32 s13, s13, 19
	s_mul_i32 s14, s13, 176
	s_sub_u32 s14, s12, s14
	s_mul_i32 s15, s13, 0x2c0000
	s_lshl_b32 s16, s14, 7
	s_add_u32 s15, s15, s16
	s_add_u32 s10, s4, s15
	s_addc_u32 s11, s5, 0
	global_load_dword v40, v34, s[10:11] nt
	s_add_u32 s10, s10, 0x58000
	s_addc_u32 s11, s11, 0
	global_load_dword v41, v34, s[10:11] nt
	s_add_u32 s10, s10, 0x58000
	s_addc_u32 s11, s11, 0
	global_load_dword v42, v34, s[10:11] nt
	s_add_u32 s10, s10, 0x58000
	s_addc_u32 s11, s11, 0
	global_load_dword v43, v34, s[10:11] nt
	s_add_u32 s10, s10, 0x58000
	s_addc_u32 s11, s11, 0
	global_load_dword v44, v34, s[10:11] nt
	s_add_u32 s10, s10, 0x58000
	s_addc_u32 s11, s11, 0
	global_load_dword v45, v34, s[10:11] nt
	s_add_u32 s10, s10, 0x58000
	s_addc_u32 s11, s11, 0
	global_load_dword v46, v34, s[10:11] nt
	s_add_u32 s10, s10, 0x58000
	s_addc_u32 s11, s11, 0
	global_load_dword v47, v34, s[10:11] nt
	s_mul_i32 s12, s21, 1
	s_add_u32 s12, s12, s8
	s_cmp_ge_u32 s12, 0x1600
	s_cbranch_scc1 .Lcv_wf1_l1_p0_ld_done
	s_mul_i32 s12, s21, 1
	s_add_u32 s12, s12, s8
	s_mul_i32 s13, s12, 0xba3
	s_lshr_b32 s13, s13, 19
	s_mul_i32 s14, s13, 176
	s_sub_u32 s14, s12, s14
	s_mul_i32 s15, s13, 0x2c0000
	s_lshl_b32 s16, s14, 7
	s_add_u32 s15, s15, s16
	s_add_u32 s10, s4, s15
	s_addc_u32 s11, s5, 0
	global_load_dword v48, v34, s[10:11] nt
	s_add_u32 s10, s10, 0x58000
	s_addc_u32 s11, s11, 0
	global_load_dword v49, v34, s[10:11] nt
	s_add_u32 s10, s10, 0x58000
	s_addc_u32 s11, s11, 0
	global_load_dword v50, v34, s[10:11] nt
	s_add_u32 s10, s10, 0x58000
	s_addc_u32 s11, s11, 0
	global_load_dword v51, v34, s[10:11] nt
	s_add_u32 s10, s10, 0x58000
	s_addc_u32 s11, s11, 0
	global_load_dword v52, v34, s[10:11] nt
	s_add_u32 s10, s10, 0x58000
	s_addc_u32 s11, s11, 0
	global_load_dword v53, v34, s[10:11] nt
	s_add_u32 s10, s10, 0x58000
	s_addc_u32 s11, s11, 0
	global_load_dword v54, v34, s[10:11] nt
	s_add_u32 s10, s10, 0x58000
	s_addc_u32 s11, s11, 0
	global_load_dword v55, v34, s[10:11] nt
	s_mul_i32 s12, s21, 2
	s_add_u32 s12, s12, s8
	s_cmp_ge_u32 s12, 0x1600
	s_cbranch_scc1 .Lcv_wf1_l1_p0_ld_done
	s_mul_i32 s12, s21, 2
	s_add_u32 s12, s12, s8
	s_mul_i32 s13, s12, 0xba3
	s_lshr_b32 s13, s13, 19
	s_mul_i32 s14, s13, 176
	s_sub_u32 s14, s12, s14
	s_mul_i32 s15, s13, 0x2c0000
	s_lshl_b32 s16, s14, 7
	s_add_u32 s15, s15, s16
	s_add_u32 s10, s4, s15
	s_addc_u32 s11, s5, 0
	global_load_dword v56, v34, s[10:11] nt
	s_add_u32 s10, s10, 0x58000
	s_addc_u32 s11, s11, 0
	global_load_dword v57, v34, s[10:11] nt
	s_add_u32 s10, s10, 0x58000
	s_addc_u32 s11, s11, 0
	global_load_dword v58, v34, s[10:11] nt
	s_add_u32 s10, s10, 0x58000
	s_addc_u32 s11, s11, 0
	global_load_dword v59, v34, s[10:11] nt
	s_add_u32 s10, s10, 0x58000
	s_addc_u32 s11, s11, 0
	global_load_dword v60, v34, s[10:11] nt
	s_add_u32 s10, s10, 0x58000
	s_addc_u32 s11, s11, 0
	global_load_dword v61, v34, s[10:11] nt
	s_add_u32 s10, s10, 0x58000
	s_addc_u32 s11, s11, 0
	global_load_dword v62, v34, s[10:11] nt
	s_add_u32 s10, s10, 0x58000
	s_addc_u32 s11, s11, 0
	global_load_dword v63, v34, s[10:11] nt
	s_mul_i32 s12, s21, 3
	s_add_u32 s12, s12, s8
	s_cmp_ge_u32 s12, 0x1600
	s_cbranch_scc1 .Lcv_wf1_l1_p0_ld_done
	s_mul_i32 s12, s21, 3
	s_add_u32 s12, s12, s8
	s_mul_i32 s13, s12, 0xba3
	s_lshr_b32 s13, s13, 19
	s_mul_i32 s14, s13, 176
	s_sub_u32 s14, s12, s14
	s_mul_i32 s15, s13, 0x2c0000
	s_lshl_b32 s16, s14, 7
	s_add_u32 s15, s15, s16
	s_add_u32 s10, s4, s15
	s_addc_u32 s11, s5, 0
	global_load_dword v64, v34, s[10:11] nt
	s_add_u32 s10, s10, 0x58000
	s_addc_u32 s11, s11, 0
	global_load_dword v65, v34, s[10:11] nt
	s_add_u32 s10, s10, 0x58000
	s_addc_u32 s11, s11, 0
	global_load_dword v66, v34, s[10:11] nt
	s_add_u32 s10, s10, 0x58000
	s_addc_u32 s11, s11, 0
	global_load_dword v67, v34, s[10:11] nt
	s_add_u32 s10, s10, 0x58000
	s_addc_u32 s11, s11, 0
	global_load_dword v68, v34, s[10:11] nt
	s_add_u32 s10, s10, 0x58000
	s_addc_u32 s11, s11, 0
	global_load_dword v69, v34, s[10:11] nt
	s_add_u32 s10, s10, 0x58000
	s_addc_u32 s11, s11, 0
	global_load_dword v70, v34, s[10:11] nt
	s_add_u32 s10, s10, 0x58000
	s_addc_u32 s11, s11, 0
	global_load_dword v71, v34, s[10:11] nt
; DI unsigned cvtpk(float lo, float hi) { unsigned r; asm volatile("v_cvt_pk_bf16_f32 %0, %1, %2" : "=v"(r) : "v"(lo), "v"(hi)); return r; }
; template <class Map>
; DI void conv_T(bf16_t* __restrict__ dst, const float* __restrict__ src, int K, int ldsrc, int nphys, Map map, const float* __restrict__ kscale, float* tile) {
;     ...
;     const int nn = tid & 63, sc = map(n0 + nn);
; #pragma unroll
;     for (int i = 0; i < 8; ++i) { const int kk = i * 8 + (tid >> 6);
;       float v = sc >= 0 ? __builtin_nontemporal_load(&src[(size_t)(k0 + kk) * ldsrc + sc]) : 0.f;
;       if (kscale) v *= kscale[k0 + kk];
;       tile[kk * 65 + nn] = v; }
;     __syncthreads();
;     const int np = tid >> 3, ks = tid & 7;
;     float v[8];
; #pragma unroll
;     for (int j = 0; j < 8; ++j) v[j] = tile[(ks * 8 + j) * 65 + np];
;     u32x4 w = {cvtpk(v[0], v[1]), cvtpk(v[2], v[3]), cvtpk(v[4], v[5]), cvtpk(v[6], v[7])};
;     *(u32x4*)(dst + (size_t)(n0 + np) * K + k0 + ks * 8) = w;
.Lcv_wf1_l1_p0_ld_done:
	s_waitcnt vmcnt(0)
	ds_write_b32 v30, v40
	ds_write_b32 v30, v41 offset:2080
	ds_write_b32 v30, v42 offset:4160
	ds_write_b32 v30, v43 offset:6240
	ds_write_b32 v30, v44 offset:8320
	ds_write_b32 v30, v45 offset:10400
	ds_write_b32 v30, v46 offset:12480
	ds_write_b32 v30, v47 offset:14560
	s_mul_i32 s12, s21, 1
	s_add_u32 s12, s12, s8
	s_cmp_ge_u32 s12, 0x1600
	s_cbranch_scc1 .Lcv_wf1_l1_p0_wr_done
	ds_write_b32 v30, v48 offset:16640
	ds_write_b32 v30, v49 offset:18720
	ds_write_b32 v30, v50 offset:20800
	ds_write_b32 v30, v51 offset:22880
	ds_write_b32 v30, v52 offset:24960
	ds_write_b32 v30, v53 offset:27040
	ds_write_b32 v30, v54 offset:29120
	ds_write_b32 v30, v55 offset:31200
	s_mul_i32 s12, s21, 2
	s_add_u32 s12, s12, s8
	s_cmp_ge_u32 s12, 0x1600
	s_cbranch_scc1 .Lcv_wf1_l1_p0_wr_done
	ds_write_b32 v30, v56 offset:33280
	ds_write_b32 v30, v57 offset:35360
	ds_write_b32 v30, v58 offset:37440
	ds_write_b32 v30, v59 offset:39520
	ds_write_b32 v30, v60 offset:41600
	ds_write_b32 v30, v61 offset:43680
	ds_write_b32 v30, v62 offset:45760
	ds_write_b32 v30, v63 offset:47840
	s_mul_i32 s12, s21, 3
	s_add_u32 s12, s12, s8
	s_cmp_ge_u32 s12, 0x1600
	s_cbranch_scc1 .Lcv_wf1_l1_p0_wr_done
	ds_write_b32 v30, v64 offset:49920
	ds_write_b32 v30, v65 offset:52000
	ds_write_b32 v30, v66 offset:54080
	ds_write_b32 v30, v67 offset:56160
	ds_write_b32 v30, v68 offset:58240
	ds_write_b32 v30, v69 offset:60320
	ds_write_b32 v30, v70 offset:62400
	ds_write_b32 v30, v71 offset:64480
.Lcv_wf1_l1_p0_wr_done:
	s_waitcnt lgkmcnt(0)
	s_barrier
	ds_read_b32 v40, v32
	ds_read_b32 v41, v32 offset:260
	ds_read_b32 v42, v32 offset:520
	ds_read_b32 v43, v32 offset:780
	ds_read_b32 v44, v32 offset:1040
	ds_read_b32 v45, v32 offset:1300
	ds_read_b32 v46, v32 offset:1560
	ds_read_b32 v47, v32 offset:1820
	s_mul_i32 s12, s21, 1
	s_add_u32 s12, s12, s8
	s_cmp_ge_u32 s12, 0x1600
	s_cbranch_scc1 .Lcv_wf1_l1_p0_rd_done
	ds_read_b32 v48, v32 offset:16640
	ds_read_b32 v49, v32 offset:16900
	ds_read_b32 v50, v32 offset:17160
	ds_read_b32 v51, v32 offset:17420
	ds_read_b32 v52, v32 offset:17680
	ds_read_b32 v53, v32 offset:17940
	ds_read_b32 v54, v32 offset:18200
	ds_read_b32 v55, v32 offset:18460
	s_mul_i32 s12, s21, 2
	s_add_u32 s12, s12, s8
	s_cmp_ge_u32 s12, 0x1600
	s_cbranch_scc1 .Lcv_wf1_l1_p0_rd_done
	ds_read_b32 v56, v32 offset:33280
	ds_read_b32 v57, v32 offset:33540
	ds_read_b32 v58, v32 offset:33800
	ds_read_b32 v59, v32 offset:34060
	ds_read_b32 v60, v32 offset:34320
	ds_read_b32 v61, v32 offset:34580
	ds_read_b32 v62, v32 offset:34840
	ds_read_b32 v63, v32 offset:35100
	s_mul_i32 s12, s21, 3
	s_add_u32 s12, s12, s8
	s_cmp_ge_u32 s12, 0x1600
	s_cbranch_scc1 .Lcv_wf1_l1_p0_rd_done
	ds_read_b32 v64, v32 offset:49920
	ds_read_b32 v65, v32 offset:50180
	ds_read_b32 v66, v32 offset:50440
	ds_read_b32 v67, v32 offset:50700
	ds_read_b32 v68, v32 offset:50960
	ds_read_b32 v69, v32 offset:51220
	ds_read_b32 v70, v32 offset:51480
	ds_read_b32 v71, v32 offset:51740
.Lcv_wf1_l1_p0_rd_done:
	s_waitcnt lgkmcnt(0)
	s_mov_b32 s12, s8
	s_mul_i32 s13, s12, 0xba3
	s_lshr_b32 s13, s13, 19
	s_mul_i32 s14, s13, 176
	s_sub_u32 s14, s12, s14
	s_mul_i32 s15, s14, 0x40000
	s_lshl_b32 s16, s13, 7
	s_add_u32 s15, s15, s16
	s_add_u32 s10, s6, s15
	s_addc_u32 s11, s7, 0
	v_cvt_pk_bf16_f32 v72, v40, v41
	v_cvt_pk_bf16_f32 v73, v42, v43
	v_cvt_pk_bf16_f32 v74, v44, v45
	v_cvt_pk_bf16_f32 v75, v46, v47
	global_store_dwordx4 v35, v[72:75], s[10:11]
	s_mul_i32 s12, s21, 1
	s_add_u32 s12, s12, s8
	s_cmp_ge_u32 s12, 0x1600
	s_cbranch_scc1 .Lcv_wf1_l1_p0_st_done
	s_mul_i32 s12, s21, 1
	s_add_u32 s12, s12, s8
	s_mul_i32 s13, s12, 0xba3
	s_lshr_b32 s13, s13, 19
	s_mul_i32 s14, s13, 176
	s_sub_u32 s14, s12, s14
	s_mul_i32 s15, s14, 0x40000
	s_lshl_b32 s16, s13, 7
	s_add_u32 s15, s15, s16
	s_add_u32 s10, s6, s15
	s_addc_u32 s11, s7, 0
	v_cvt_pk_bf16_f32 v76, v48, v49
	v_cvt_pk_bf16_f32 v77, v50, v51
	v_cvt_pk_bf16_f32 v78, v52, v53
	v_cvt_pk_bf16_f32 v79, v54, v55
	global_store_dwordx4 v35, v[76:79], s[10:11]
	s_mul_i32 s12, s21, 2
	s_add_u32 s12, s12, s8
	s_cmp_ge_u32 s12, 0x1600
	s_cbranch_scc1 .Lcv_wf1_l1_p0_st_done
	s_mul_i32 s12, s21, 2
	s_add_u32 s12, s12, s8
	s_mul_i32 s13, s12, 0xba3
	s_lshr_b32 s13, s13, 19
	s_mul_i32 s14, s13, 176
	s_sub_u32 s14, s12, s14
	s_mul_i32 s15, s14, 0x40000
	s_lshl_b32 s16, s13, 7
	s_add_u32 s15, s15, s16
	s_add_u32 s10, s6, s15
	s_addc_u32 s11, s7, 0
	v_cvt_pk_bf16_f32 v80, v56, v57
	v_cvt_pk_bf16_f32 v81, v58, v59
	v_cvt_pk_bf16_f32 v82, v60, v61
	v_cvt_pk_bf16_f32 v83, v62, v63
	global_store_dwordx4 v35, v[80:83], s[10:11]
	s_mul_i32 s12, s21, 3
	s_add_u32 s12, s12, s8
	s_cmp_ge_u32 s12, 0x1600
	s_cbranch_scc1 .Lcv_wf1_l1_p0_st_done
	s_mul_i32 s12, s21, 3
	s_add_u32 s12, s12, s8
	s_mul_i32 s13, s12, 0xba3
	s_lshr_b32 s13, s13, 19
	s_mul_i32 s14, s13, 176
	s_sub_u32 s14, s12, s14
	s_mul_i32 s15, s14, 0x40000
	s_lshl_b32 s16, s13, 7
	s_add_u32 s15, s15, s16
	s_add_u32 s10, s6, s15
	s_addc_u32 s11, s7, 0
	v_cvt_pk_bf16_f32 v84, v64, v65
	v_cvt_pk_bf16_f32 v85, v66, v67
	v_cvt_pk_bf16_f32 v86, v68, v69
	v_cvt_pk_bf16_f32 v87, v70, v71
	global_store_dwordx4 v35, v[84:87], s[10:11]
; DI int lbid() { int b = blockIdx.x; asm volatile("" : "+s"(b)); return b; }
; template <class Map>
; DI void conv_T(bf16_t* __restrict__ dst, const float* __restrict__ src, int K, int ldsrc, int nphys, Map map, const float* __restrict__ kscale, float* tile) {
;     ...
;   for (int tl = lbid(); tl < ntiles; tl += gridDim.x) {
;     const int k0 = (tl / ntn) << 6, n0 = (tl % ntn) << 6;
;     const int nn = tid & 63, sc = map(n0 + nn);
; #pragma unroll
;     for (int i = 0; i < 8; ++i) { const int kk = i * 8 + (tid >> 6);
;       float v = sc >= 0 ? __builtin_nontemporal_load(&src[(size_t)(k0 + kk) * ldsrc + sc]) : 0.f;
;       if (kscale) v *= kscale[k0 + kk];
;       tile[kk * 65 + nn] = v; }
.Lcv_wf1_l1_p0_st_done:
	s_lshl_b32 s12, s21, 2
	s_add_u32 s8, s8, s12
	s_cmp_ge_u32 s8, 0x1600
	s_cbranch_scc1 .Lcv_wf1_l1_end
	s_mov_b32 s12, s8
	s_mul_i32 s13, s12, 0xba3
	s_lshr_b32 s13, s13, 19
	s_mul_i32 s14, s13, 176
	s_sub_u32 s14, s12, s14
	s_mul_i32 s15, s13, 0x2c0000
	s_lshl_b32 s16, s14, 7
	s_add_u32 s15, s15, s16
	s_add_u32 s10, s4, s15
	s_addc_u32 s11, s5, 0
	global_load_dword v40, v34, s[10:11] nt
	s_add_u32 s10, s10, 0x58000
	s_addc_u32 s11, s11, 0
	global_load_dword v41, v34, s[10:11] nt
	s_add_u32 s10, s10, 0x58000
	s_addc_u32 s11, s11, 0
	global_load_dword v42, v34, s[10:11] nt
	s_add_u32 s10, s10, 0x58000
	s_addc_u32 s11, s11, 0
	global_load_dword v43, v34, s[10:11] nt
	s_add_u32 s10, s10, 0x58000
	s_addc_u32 s11, s11, 0
	global_load_dword v44, v34, s[10:11] nt
	s_add_u32 s10, s10, 0x58000
	s_addc_u32 s11, s11, 0
	global_load_dword v45, v34, s[10:11] nt
	s_add_u32 s10, s10, 0x58000
	s_addc_u32 s11, s11, 0
	global_load_dword v46, v34, s[10:11] nt
	s_add_u32 s10, s10, 0x58000
	s_addc_u32 s11, s11, 0
	global_load_dword v47, v34, s[10:11] nt
	s_mul_i32 s12, s21, 1
	s_add_u32 s12, s12, s8
	s_cmp_ge_u32 s12, 0x1600
	s_cbranch_scc1 .Lcv_wf1_l1_p1_ld_done
	s_mul_i32 s12, s21, 1
	s_add_u32 s12, s12, s8
	s_mul_i32 s13, s12, 0xba3
	s_lshr_b32 s13, s13, 19
	s_mul_i32 s14, s13, 176
	s_sub_u32 s14, s12, s14
	s_mul_i32 s15, s13, 0x2c0000
	s_lshl_b32 s16, s14, 7
	s_add_u32 s15, s15, s16
	s_add_u32 s10, s4, s15
	s_addc_u32 s11, s5, 0
	global_load_dword v48, v34, s[10:11] nt
	s_add_u32 s10, s10, 0x58000
	s_addc_u32 s11, s11, 0
	global_load_dword v49, v34, s[10:11] nt
	s_add_u32 s10, s10, 0x58000
	s_addc_u32 s11, s11, 0
	global_load_dword v50, v34, s[10:11] nt
	s_add_u32 s10, s10, 0x58000
	s_addc_u32 s11, s11, 0
	global_load_dword v51, v34, s[10:11] nt
	s_add_u32 s10, s10, 0x58000
	s_addc_u32 s11, s11, 0
	global_load_dword v52, v34, s[10:11] nt
	s_add_u32 s10, s10, 0x58000
	s_addc_u32 s11, s11, 0
	global_load_dword v53, v34, s[10:11] nt
	s_add_u32 s10, s10, 0x58000
	s_addc_u32 s11, s11, 0
	global_load_dword v54, v34, s[10:11] nt
	s_add_u32 s10, s10, 0x58000
	s_addc_u32 s11, s11, 0
	global_load_dword v55, v34, s[10:11] nt
	s_mul_i32 s12, s21, 2
	s_add_u32 s12, s12, s8
	s_cmp_ge_u32 s12, 0x1600
	s_cbranch_scc1 .Lcv_wf1_l1_p1_ld_done
	s_mul_i32 s12, s21, 2
	s_add_u32 s12, s12, s8
	s_mul_i32 s13, s12, 0xba3
	s_lshr_b32 s13, s13, 19
	s_mul_i32 s14, s13, 176
	s_sub_u32 s14, s12, s14
	s_mul_i32 s15, s13, 0x2c0000
	s_lshl_b32 s16, s14, 7
	s_add_u32 s15, s15, s16
	s_add_u32 s10, s4, s15
	s_addc_u32 s11, s5, 0
	global_load_dword v56, v34, s[10:11] nt
	s_add_u32 s10, s10, 0x58000
	s_addc_u32 s11, s11, 0
	global_load_dword v57, v34, s[10:11] nt
	s_add_u32 s10, s10, 0x58000
	s_addc_u32 s11, s11, 0
	global_load_dword v58, v34, s[10:11] nt
	s_add_u32 s10, s10, 0x58000
	s_addc_u32 s11, s11, 0
	global_load_dword v59, v34, s[10:11] nt
	s_add_u32 s10, s10, 0x58000
	s_addc_u32 s11, s11, 0
	global_load_dword v60, v34, s[10:11] nt
	s_add_u32 s10, s10, 0x58000
	s_addc_u32 s11, s11, 0
	global_load_dword v61, v34, s[10:11] nt
	s_add_u32 s10, s10, 0x58000
	s_addc_u32 s11, s11, 0
	global_load_dword v62, v34, s[10:11] nt
	s_add_u32 s10, s10, 0x58000
	s_addc_u32 s11, s11, 0
	global_load_dword v63, v34, s[10:11] nt
	s_mul_i32 s12, s21, 3
	s_add_u32 s12, s12, s8
	s_cmp_ge_u32 s12, 0x1600
	s_cbranch_scc1 .Lcv_wf1_l1_p1_ld_done
	s_mul_i32 s12, s21, 3
	s_add_u32 s12, s12, s8
	s_mul_i32 s13, s12, 0xba3
	s_lshr_b32 s13, s13, 19
	s_mul_i32 s14, s13, 176
	s_sub_u32 s14, s12, s14
	s_mul_i32 s15, s13, 0x2c0000
	s_lshl_b32 s16, s14, 7
	s_add_u32 s15, s15, s16
	s_add_u32 s10, s4, s15
	s_addc_u32 s11, s5, 0
	global_load_dword v64, v34, s[10:11] nt
	s_add_u32 s10, s10, 0x58000
	s_addc_u32 s11, s11, 0
	global_load_dword v65, v34, s[10:11] nt
	s_add_u32 s10, s10, 0x58000
	s_addc_u32 s11, s11, 0
	global_load_dword v66, v34, s[10:11] nt
	s_add_u32 s10, s10, 0x58000
	s_addc_u32 s11, s11, 0
	global_load_dword v67, v34, s[10:11] nt
	s_add_u32 s10, s10, 0x58000
	s_addc_u32 s11, s11, 0
	global_load_dword v68, v34, s[10:11] nt
	s_add_u32 s10, s10, 0x58000
	s_addc_u32 s11, s11, 0
	global_load_dword v69, v34, s[10:11] nt
	s_add_u32 s10, s10, 0x58000
	s_addc_u32 s11, s11, 0
	global_load_dword v70, v34, s[10:11] nt
	s_add_u32 s10, s10, 0x58000
	s_addc_u32 s11, s11, 0
	global_load_dword v71, v34, s[10:11] nt
; template <class Map>
; DI void conv_T(bf16_t* __restrict__ dst, const float* __restrict__ src, int K, int ldsrc, int nphys, Map map, const float* __restrict__ kscale, float* tile) {
;     ...
;     for (int i = 0; i < 8; ++i) { const int kk = i * 8 + (tid >> 6);
;       float v = sc >= 0 ? __builtin_nontemporal_load(&src[(size_t)(k0 + kk) * ldsrc + sc]) : 0.f;
;       if (kscale) v *= kscale[k0 + kk];
;       tile[kk * 65 + nn] = v; }
;     __syncthreads();
;     const int np = tid >> 3, ks = tid & 7;
;     float v[8];
; #pragma unroll
;     for (int j = 0; j < 8; ++j) v[j] = tile[(ks * 8 + j) * 65 + np];
.Lcv_wf1_l1_p1_ld_done:
	s_waitcnt vmcnt(0)
	ds_write_b32 v31, v40
	ds_write_b32 v31, v41 offset:2080
	ds_write_b32 v31, v42 offset:4160
	ds_write_b32 v31, v43 offset:6240
	ds_write_b32 v31, v44 offset:8320
	ds_write_b32 v31, v45 offset:10400
	ds_write_b32 v31, v46 offset:12480
	ds_write_b32 v31, v47 offset:14560
	s_mul_i32 s12, s21, 1
	s_add_u32 s12, s12, s8
	s_cmp_ge_u32 s12, 0x1600
	s_cbranch_scc1 .Lcv_wf1_l1_p1_wr_done
	ds_write_b32 v31, v48 offset:16640
	ds_write_b32 v31, v49 offset:18720
	ds_write_b32 v31, v50 offset:20800
	ds_write_b32 v31, v51 offset:22880
	ds_write_b32 v31, v52 offset:24960
	ds_write_b32 v31, v53 offset:27040
	ds_write_b32 v31, v54 offset:29120
	ds_write_b32 v31, v55 offset:31200
	s_mul_i32 s12, s21, 2
	s_add_u32 s12, s12, s8
	s_cmp_ge_u32 s12, 0x1600
	s_cbranch_scc1 .Lcv_wf1_l1_p1_wr_done
	ds_write_b32 v31, v56 offset:33280
	ds_write_b32 v31, v57 offset:35360
	ds_write_b32 v31, v58 offset:37440
	ds_write_b32 v31, v59 offset:39520
	ds_write_b32 v31, v60 offset:41600
	ds_write_b32 v31, v61 offset:43680
	ds_write_b32 v31, v62 offset:45760
	ds_write_b32 v31, v63 offset:47840
	s_mul_i32 s12, s21, 3
	s_add_u32 s12, s12, s8
	s_cmp_ge_u32 s12, 0x1600
	s_cbranch_scc1 .Lcv_wf1_l1_p1_wr_done
	ds_write_b32 v31, v64 offset:49920
	ds_write_b32 v31, v65 offset:52000
	ds_write_b32 v31, v66 offset:54080
	ds_write_b32 v31, v67 offset:56160
	ds_write_b32 v31, v68 offset:58240
	ds_write_b32 v31, v69 offset:60320
	ds_write_b32 v31, v70 offset:62400
	ds_write_b32 v31, v71 offset:64480
.Lcv_wf1_l1_p1_wr_done:
	s_waitcnt lgkmcnt(0)
	s_barrier
	ds_read_b32 v40, v33
	ds_read_b32 v41, v33 offset:260
	ds_read_b32 v42, v33 offset:520
	ds_read_b32 v43, v33 offset:780
	ds_read_b32 v44, v33 offset:1040
	ds_read_b32 v45, v33 offset:1300
	ds_read_b32 v46, v33 offset:1560
	ds_read_b32 v47, v33 offset:1820
	s_mul_i32 s12, s21, 1
	s_add_u32 s12, s12, s8
	s_cmp_ge_u32 s12, 0x1600
	s_cbranch_scc1 .Lcv_wf1_l1_p1_rd_done
	ds_read_b32 v48, v33 offset:16640
	ds_read_b32 v49, v33 offset:16900
	ds_read_b32 v50, v33 offset:17160
	ds_read_b32 v51, v33 offset:17420
	ds_read_b32 v52, v33 offset:17680
	ds_read_b32 v53, v33 offset:17940
	ds_read_b32 v54, v33 offset:18200
	ds_read_b32 v55, v33 offset:18460
	s_mul_i32 s12, s21, 2
	s_add_u32 s12, s12, s8
	s_cmp_ge_u32 s12, 0x1600
	s_cbranch_scc1 .Lcv_wf1_l1_p1_rd_done
	ds_read_b32 v56, v33 offset:33280
	ds_read_b32 v57, v33 offset:33540
	ds_read_b32 v58, v33 offset:33800
	ds_read_b32 v59, v33 offset:34060
	ds_read_b32 v60, v33 offset:34320
	ds_read_b32 v61, v33 offset:34580
	ds_read_b32 v62, v33 offset:34840
	ds_read_b32 v63, v33 offset:35100
	s_mul_i32 s12, s21, 3
	s_add_u32 s12, s12, s8
	s_cmp_ge_u32 s12, 0x1600
	s_cbranch_scc1 .Lcv_wf1_l1_p1_rd_done
	ds_read_b32 v64, v33 offset:49920
	ds_read_b32 v65, v33 offset:50180
	ds_read_b32 v66, v33 offset:50440
	ds_read_b32 v67, v33 offset:50700
	ds_read_b32 v68, v33 offset:50960
	ds_read_b32 v69, v33 offset:51220
	ds_read_b32 v70, v33 offset:51480
	ds_read_b32 v71, v33 offset:51740

; DI int ltid() { int t = threadIdx.x; asm volatile("" : "+v"(t)); return t; }
; DI int lbid() { int b = blockIdx.x; asm volatile("" : "+s"(b)); return b; }
; template <class Map>
; DI void conv_T(bf16_t* __restrict__ dst, const float* __restrict__ src, int K, int ldsrc, int nphys, Map map, const float* __restrict__ kscale, float* tile) {
;   const int tid = ltid(), ntn = nphys >> 6, ntiles = (K >> 6) * ntn;
;   for (int tl = lbid(); tl < ntiles; tl += gridDim.x) {
;     const int k0 = (tl / ntn) << 6, n0 = (tl % ntn) << 6;
;     const int nn = tid & 63, sc = map(n0 + nn);
; #pragma unroll
;     for (int i = 0; i < 8; ++i) { const int kk = i * 8 + (tid >> 6);
;       float v = sc >= 0 ? __builtin_nontemporal_load(&src[(size_t)(k0 + kk) * ldsrc + sc]) : 0.f;
;       if (kscale) v *= kscale[k0 + kk];
;       tile[kk * 65 + nn] = v; }
; DI void convert_layer(const Params& p, int l, float* tile) {
;     ...
;   conv_T((bf16_t*)(ws + O_WF2), p.w_f2 + (size_t)l * DFF * 2048, DFF, 2048, 2048, MapId{0}, nullptr, tile);
.Lcv_wf1_l1_p1_st_done:
	s_lshl_b32 s12, s21, 2
	s_add_u32 s8, s8, s12
	s_cmp_ge_u32 s8, 0x1600
	s_cbranch_scc0 .Lcv_wf1_l1_loop
.Lcv_wf1_l1_end:
	s_waitcnt lgkmcnt(0)
	s_barrier
	v_readlane_b32 s4, v249, 14
	v_readlane_b32 s5, v249, 15
	s_add_u32 s4, s4, 0x2c00000
	s_addc_u32 s5, s5, 0
	s_add_u32 s6, s18, 0x7c00000
	s_addc_u32 s7, s19, 0
	v_lshrrev_b32_e32 v36, 6, v248
	v_and_b32_e32 v37, 63, v248
	v_mov_b32_e32 v38, 0x2000
	v_mul_u32_u24_e32 v34, v36, v38
	v_lshl_add_u32 v34, v37, 2, v34
	v_lshrrev_b32_e32 v36, 3, v248
	v_and_b32_e32 v37, 7, v248
	v_mov_b32_e32 v38, 0x2c00
	v_mul_u32_u24_e32 v35, v36, v38
	v_lshl_add_u32 v35, v37, 4, v35
	s_mov_b32 s8, s20
	s_cmp_ge_u32 s8, 0xb00
	s_cbranch_scc1 .Lcv_wf2_l1_end
.Lcv_wf2_l1_loop:
	s_mov_b32 s12, s8
	s_lshr_b32 s13, s12, 5
	s_and_b32 s14, s12, 31
	s_mul_i32 s15, s13, 0x80000
	s_lshl_b32 s16, s14, 8
	s_add_u32 s15, s15, s16
	s_add_u32 s10, s4, s15
	s_addc_u32 s11, s5, 0
	global_load_dword v40, v34, s[10:11] nt
	s_add_u32 s10, s10, 0x10000
	s_addc_u32 s11, s11, 0
	global_load_dword v41, v34, s[10:11] nt
	s_add_u32 s10, s10, 0x10000
	s_addc_u32 s11, s11, 0
	global_load_dword v42, v34, s[10:11] nt
	s_add_u32 s10, s10, 0x10000
	s_addc_u32 s11, s11, 0
	global_load_dword v43, v34, s[10:11] nt
	s_add_u32 s10, s10, 0x10000
	s_addc_u32 s11, s11, 0
	global_load_dword v44, v34, s[10:11] nt
	s_add_u32 s10, s10, 0x10000
	s_addc_u32 s11, s11, 0
	global_load_dword v45, v34, s[10:11] nt
	s_add_u32 s10, s10, 0x10000
	s_addc_u32 s11, s11, 0
	global_load_dword v46, v34, s[10:11] nt
	s_add_u32 s10, s10, 0x10000
	s_addc_u32 s11, s11, 0
	global_load_dword v47, v34, s[10:11] nt
	s_mul_i32 s12, s21, 1
	s_add_u32 s12, s12, s8
	s_cmp_ge_u32 s12, 0xb00
	s_cbranch_scc1 .Lcv_wf2_l1_p0_ld_done
	s_mul_i32 s12, s21, 1
	s_add_u32 s12, s12, s8
	s_lshr_b32 s13, s12, 5
	s_and_b32 s14, s12, 31
	s_mul_i32 s15, s13, 0x80000
	s_lshl_b32 s16, s14, 8
	s_add_u32 s15, s15, s16
	s_add_u32 s10, s4, s15
	s_addc_u32 s11, s5, 0
	global_load_dword v48, v34, s[10:11] nt
	s_add_u32 s10, s10, 0x10000
	s_addc_u32 s11, s11, 0
	global_load_dword v49, v34, s[10:11] nt
	s_add_u32 s10, s10, 0x10000
	s_addc_u32 s11, s11, 0
	global_load_dword v50, v34, s[10:11] nt
	s_add_u32 s10, s10, 0x10000
	s_addc_u32 s11, s11, 0
	global_load_dword v51, v34, s[10:11] nt
	s_add_u32 s10, s10, 0x10000
	s_addc_u32 s11, s11, 0
	global_load_dword v52, v34, s[10:11] nt
	s_add_u32 s10, s10, 0x10000
	s_addc_u32 s11, s11, 0
	global_load_dword v53, v34, s[10:11] nt
	s_add_u32 s10, s10, 0x10000
	s_addc_u32 s11, s11, 0
	global_load_dword v54, v34, s[10:11] nt
	s_add_u32 s10, s10, 0x10000
	s_addc_u32 s11, s11, 0
	global_load_dword v55, v34, s[10:11] nt
	s_mul_i32 s12, s21, 2
	s_add_u32 s12, s12, s8
	s_cmp_ge_u32 s12, 0xb00
	s_cbranch_scc1 .Lcv_wf2_l1_p0_ld_done
	s_mul_i32 s12, s21, 2
	s_add_u32 s12, s12, s8
	s_lshr_b32 s13, s12, 5
	s_and_b32 s14, s12, 31
	s_mul_i32 s15, s13, 0x80000
	s_lshl_b32 s16, s14, 8
	s_add_u32 s15, s15, s16
	s_add_u32 s10, s4, s15
	s_addc_u32 s11, s5, 0
	global_load_dword v56, v34, s[10:11] nt
	s_add_u32 s10, s10, 0x10000
	s_addc_u32 s11, s11, 0
	global_load_dword v57, v34, s[10:11] nt
	s_add_u32 s10, s10, 0x10000
	s_addc_u32 s11, s11, 0
	global_load_dword v58, v34, s[10:11] nt
	s_add_u32 s10, s10, 0x10000
	s_addc_u32 s11, s11, 0
	global_load_dword v59, v34, s[10:11] nt
	s_add_u32 s10, s10, 0x10000
	s_addc_u32 s11, s11, 0
	global_load_dword v60, v34, s[10:11] nt
	s_add_u32 s10, s10, 0x10000
	s_addc_u32 s11, s11, 0
	global_load_dword v61, v34, s[10:11] nt
	s_add_u32 s10, s10, 0x10000
	s_addc_u32 s11, s11, 0
	global_load_dword v62, v34, s[10:11] nt
	s_add_u32 s10, s10, 0x10000
	s_addc_u32 s11, s11, 0
	global_load_dword v63, v34, s[10:11] nt
	s_mul_i32 s12, s21, 3
	s_add_u32 s12, s12, s8
	s_cmp_ge_u32 s12, 0xb00
	s_cbranch_scc1 .Lcv_wf2_l1_p0_ld_done
	s_mul_i32 s12, s21, 3
	s_add_u32 s12, s12, s8
	s_lshr_b32 s13, s12, 5
	s_and_b32 s14, s12, 31
	s_mul_i32 s15, s13, 0x80000
	s_lshl_b32 s16, s14, 8
	s_add_u32 s15, s15, s16
	s_add_u32 s10, s4, s15
	s_addc_u32 s11, s5, 0
	global_load_dword v64, v34, s[10:11] nt
	s_add_u32 s10, s10, 0x10000
	s_addc_u32 s11, s11, 0
	global_load_dword v65, v34, s[10:11] nt
	s_add_u32 s10, s10, 0x10000
	s_addc_u32 s11, s11, 0
	global_load_dword v66, v34, s[10:11] nt
	s_add_u32 s10, s10, 0x10000
	s_addc_u32 s11, s11, 0
	global_load_dword v67, v34, s[10:11] nt
	s_add_u32 s10, s10, 0x10000
	s_addc_u32 s11, s11, 0
	global_load_dword v68, v34, s[10:11] nt
	s_add_u32 s10, s10, 0x10000
	s_addc_u32 s11, s11, 0
	global_load_dword v69, v34, s[10:11] nt
	s_add_u32 s10, s10, 0x10000
	s_addc_u32 s11, s11, 0
	global_load_dword v70, v34, s[10:11] nt
	s_add_u32 s10, s10, 0x10000
	s_addc_u32 s11, s11, 0
	global_load_dword v71, v34, s[10:11] nt
.Lcv_wf2_l1_p0_ld_done:
	s_waitcnt vmcnt(0)
	ds_write_b32 v30, v40
	ds_write_b32 v30, v41 offset:2080
	ds_write_b32 v30, v42 offset:4160
	ds_write_b32 v30, v43 offset:6240
	ds_write_b32 v30, v44 offset:8320
	ds_write_b32 v30, v45 offset:10400
	ds_write_b32 v30, v46 offset:12480
	ds_write_b32 v30, v47 offset:14560
	s_mul_i32 s12, s21, 1
	s_add_u32 s12, s12, s8
	s_cmp_ge_u32 s12, 0xb00
	s_cbranch_scc1 .Lcv_wf2_l1_p0_wr_done
	ds_write_b32 v30, v48 offset:16640
	ds_write_b32 v30, v49 offset:18720
	ds_write_b32 v30, v50 offset:20800
	ds_write_b32 v30, v51 offset:22880
	ds_write_b32 v30, v52 offset:24960
	ds_write_b32 v30, v53 offset:27040
	ds_write_b32 v30, v54 offset:29120
	ds_write_b32 v30, v55 offset:31200
	s_mul_i32 s12, s21, 2
	s_add_u32 s12, s12, s8
	s_cmp_ge_u32 s12, 0xb00
	s_cbranch_scc1 .Lcv_wf2_l1_p0_wr_done
	ds_write_b32 v30, v56 offset:33280
	ds_write_b32 v30, v57 offset:35360
	ds_write_b32 v30, v58 offset:37440
	ds_write_b32 v30, v59 offset:39520
	ds_write_b32 v30, v60 offset:41600
	ds_write_b32 v30, v61 offset:43680
	ds_write_b32 v30, v62 offset:45760
	ds_write_b32 v30, v63 offset:47840
	s_mul_i32 s12, s21, 3
	s_add_u32 s12, s12, s8
	s_cmp_ge_u32 s12, 0xb00
	s_cbranch_scc1 .Lcv_wf2_l1_p0_wr_done
	ds_write_b32 v30, v64 offset:49920
	ds_write_b32 v30, v65 offset:52000
	ds_write_b32 v30, v66 offset:54080
	ds_write_b32 v30, v67 offset:56160
	ds_write_b32 v30, v68 offset:58240
	ds_write_b32 v30, v69 offset:60320
	ds_write_b32 v30, v70 offset:62400
	ds_write_b32 v30, v71 offset:64480
; DI unsigned cvtpk(float lo, float hi) { unsigned r; asm volatile("v_cvt_pk_bf16_f32 %0, %1, %2" : "=v"(r) : "v"(lo), "v"(hi)); return r; }
; template <class Map>
; DI void conv_T(bf16_t* __restrict__ dst, const float* __restrict__ src, int K, int ldsrc, int nphys, Map map, const float* __restrict__ kscale, float* tile) {
;     ...
;     const int nn = tid & 63, sc = map(n0 + nn);
; #pragma unroll
;     for (int i = 0; i < 8; ++i) { const int kk = i * 8 + (tid >> 6);
;       float v = sc >= 0 ? __builtin_nontemporal_load(&src[(size_t)(k0 + kk) * ldsrc + sc]) : 0.f;
;       if (kscale) v *= kscale[k0 + kk];
;       tile[kk * 65 + nn] = v; }
;     __syncthreads();
;     const int np = tid >> 3, ks = tid & 7;
;     float v[8];
; #pragma unroll
;     for (int j = 0; j < 8; ++j) v[j] = tile[(ks * 8 + j) * 65 + np];
;     u32x4 w = {cvtpk(v[0], v[1]), cvtpk(v[2], v[3]), cvtpk(v[4], v[5]), cvtpk(v[6], v[7])};
;     *(u32x4*)(dst + (size_t)(n0 + np) * K + k0 + ks * 8) = w;
.Lcv_wf2_l1_p0_wr_done:
	s_waitcnt lgkmcnt(0)
	s_barrier
	ds_read_b32 v40, v32
	ds_read_b32 v41, v32 offset:260
	ds_read_b32 v42, v32 offset:520
	ds_read_b32 v43, v32 offset:780
	ds_read_b32 v44, v32 offset:1040
	ds_read_b32 v45, v32 offset:1300
	ds_read_b32 v46, v32 offset:1560
	ds_read_b32 v47, v32 offset:1820
	s_mul_i32 s12, s21, 1
	s_add_u32 s12, s12, s8
	s_cmp_ge_u32 s12, 0xb00
	s_cbranch_scc1 .Lcv_wf2_l1_p0_rd_done
	ds_read_b32 v48, v32 offset:16640
	ds_read_b32 v49, v32 offset:16900
	ds_read_b32 v50, v32 offset:17160
	ds_read_b32 v51, v32 offset:17420
	ds_read_b32 v52, v32 offset:17680
	ds_read_b32 v53, v32 offset:17940
	ds_read_b32 v54, v32 offset:18200
	ds_read_b32 v55, v32 offset:18460
	s_mul_i32 s12, s21, 2
	s_add_u32 s12, s12, s8
	s_cmp_ge_u32 s12, 0xb00
	s_cbranch_scc1 .Lcv_wf2_l1_p0_rd_done
	ds_read_b32 v56, v32 offset:33280
	ds_read_b32 v57, v32 offset:33540
	ds_read_b32 v58, v32 offset:33800
	ds_read_b32 v59, v32 offset:34060
	ds_read_b32 v60, v32 offset:34320
	ds_read_b32 v61, v32 offset:34580
	ds_read_b32 v62, v32 offset:34840
	ds_read_b32 v63, v32 offset:35100
	s_mul_i32 s12, s21, 3
	s_add_u32 s12, s12, s8
	s_cmp_ge_u32 s12, 0xb00
	s_cbranch_scc1 .Lcv_wf2_l1_p0_rd_done
	ds_read_b32 v64, v32 offset:49920
	ds_read_b32 v65, v32 offset:50180
	ds_read_b32 v66, v32 offset:50440
	ds_read_b32 v67, v32 offset:50700
	ds_read_b32 v68, v32 offset:50960
	ds_read_b32 v69, v32 offset:51220
	ds_read_b32 v70, v32 offset:51480
	ds_read_b32 v71, v32 offset:51740
.Lcv_wf2_l1_p0_rd_done:
	s_waitcnt lgkmcnt(0)
	s_mov_b32 s12, s8
	s_lshr_b32 s13, s12, 5
	s_and_b32 s14, s12, 31
	s_mul_i32 s15, s14, 0xb0000
	s_lshl_b32 s16, s13, 7
	s_add_u32 s15, s15, s16
	s_add_u32 s10, s6, s15
	s_addc_u32 s11, s7, 0
	v_cvt_pk_bf16_f32 v72, v40, v41
	v_cvt_pk_bf16_f32 v73, v42, v43
	v_cvt_pk_bf16_f32 v74, v44, v45
	v_cvt_pk_bf16_f32 v75, v46, v47
	global_store_dwordx4 v35, v[72:75], s[10:11]
	s_mul_i32 s12, s21, 1
	s_add_u32 s12, s12, s8
	s_cmp_ge_u32 s12, 0xb00
	s_cbranch_scc1 .Lcv_wf2_l1_p0_st_done
	s_mul_i32 s12, s21, 1
	s_add_u32 s12, s12, s8
	s_lshr_b32 s13, s12, 5
	s_and_b32 s14, s12, 31
	s_mul_i32 s15, s14, 0xb0000
	s_lshl_b32 s16, s13, 7
	s_add_u32 s15, s15, s16
	s_add_u32 s10, s6, s15
	s_addc_u32 s11, s7, 0
	v_cvt_pk_bf16_f32 v76, v48, v49
	v_cvt_pk_bf16_f32 v77, v50, v51
	v_cvt_pk_bf16_f32 v78, v52, v53
	v_cvt_pk_bf16_f32 v79, v54, v55
	global_store_dwordx4 v35, v[76:79], s[10:11]
	s_mul_i32 s12, s21, 2
	s_add_u32 s12, s12, s8
	s_cmp_ge_u32 s12, 0xb00
	s_cbranch_scc1 .Lcv_wf2_l1_p0_st_done
	s_mul_i32 s12, s21, 2
	s_add_u32 s12, s12, s8
	s_lshr_b32 s13, s12, 5
	s_and_b32 s14, s12, 31
	s_mul_i32 s15, s14, 0xb0000
	s_lshl_b32 s16, s13, 7
	s_add_u32 s15, s15, s16
	s_add_u32 s10, s6, s15
	s_addc_u32 s11, s7, 0
	v_cvt_pk_bf16_f32 v80, v56, v57
	v_cvt_pk_bf16_f32 v81, v58, v59
	v_cvt_pk_bf16_f32 v82, v60, v61
	v_cvt_pk_bf16_f32 v83, v62, v63
	global_store_dwordx4 v35, v[80:83], s[10:11]
	s_mul_i32 s12, s21, 3
	s_add_u32 s12, s12, s8
	s_cmp_ge_u32 s12, 0xb00
	s_cbranch_scc1 .Lcv_wf2_l1_p0_st_done
	s_mul_i32 s12, s21, 3
	s_add_u32 s12, s12, s8
	s_lshr_b32 s13, s12, 5
	s_and_b32 s14, s12, 31
	s_mul_i32 s15, s14, 0xb0000
	s_lshl_b32 s16, s13, 7
	s_add_u32 s15, s15, s16
	s_add_u32 s10, s6, s15
	s_addc_u32 s11, s7, 0
	v_cvt_pk_bf16_f32 v84, v64, v65
	v_cvt_pk_bf16_f32 v85, v66, v67
	v_cvt_pk_bf16_f32 v86, v68, v69
	v_cvt_pk_bf16_f32 v87, v70, v71
	global_store_dwordx4 v35, v[84:87], s[10:11]
.Lcv_wf2_l1_p0_st_done:
	s_lshl_b32 s12, s21, 2
	s_add_u32 s8, s8, s12
	s_cmp_ge_u32 s8, 0xb00
	s_cbranch_scc1 .Lcv_wf2_l1_end
	s_mov_b32 s12, s8
	s_lshr_b32 s13, s12, 5
	s_and_b32 s14, s12, 31
	s_mul_i32 s15, s13, 0x80000
	s_lshl_b32 s16, s14, 8
	s_add_u32 s15, s15, s16
	s_add_u32 s10, s4, s15
	s_addc_u32 s11, s5, 0
	global_load_dword v40, v34, s[10:11] nt
	s_add_u32 s10, s10, 0x10000
	s_addc_u32 s11, s11, 0
	global_load_dword v41, v34, s[10:11] nt
	s_add_u32 s10, s10, 0x10000
	s_addc_u32 s11, s11, 0
	global_load_dword v42, v34, s[10:11] nt
	s_add_u32 s10, s10, 0x10000
	s_addc_u32 s11, s11, 0
	global_load_dword v43, v34, s[10:11] nt
	s_add_u32 s10, s10, 0x10000
	s_addc_u32 s11, s11, 0
	global_load_dword v44, v34, s[10:11] nt
	s_add_u32 s10, s10, 0x10000
	s_addc_u32 s11, s11, 0
	global_load_dword v45, v34, s[10:11] nt
	s_add_u32 s10, s10, 0x10000
	s_addc_u32 s11, s11, 0
	global_load_dword v46, v34, s[10:11] nt
	s_add_u32 s10, s10, 0x10000
	s_addc_u32 s11, s11, 0
	global_load_dword v47, v34, s[10:11] nt
	s_mul_i32 s12, s21, 1
	s_add_u32 s12, s12, s8
	s_cmp_ge_u32 s12, 0xb00
	s_cbranch_scc1 .Lcv_wf2_l1_p1_ld_done
	s_mul_i32 s12, s21, 1
	s_add_u32 s12, s12, s8
	s_lshr_b32 s13, s12, 5
	s_and_b32 s14, s12, 31
	s_mul_i32 s15, s13, 0x80000
	s_lshl_b32 s16, s14, 8
	s_add_u32 s15, s15, s16
	s_add_u32 s10, s4, s15
	s_addc_u32 s11, s5, 0
	global_load_dword v48, v34, s[10:11] nt
	s_add_u32 s10, s10, 0x10000
	s_addc_u32 s11, s11, 0
	global_load_dword v49, v34, s[10:11] nt
	s_add_u32 s10, s10, 0x10000
	s_addc_u32 s11, s11, 0
	global_load_dword v50, v34, s[10:11] nt
	s_add_u32 s10, s10, 0x10000
	s_addc_u32 s11, s11, 0
	global_load_dword v51, v34, s[10:11] nt
	s_add_u32 s10, s10, 0x10000
	s_addc_u32 s11, s11, 0
	global_load_dword v52, v34, s[10:11] nt
	s_add_u32 s10, s10, 0x10000
	s_addc_u32 s11, s11, 0
	global_load_dword v53, v34, s[10:11] nt
	s_add_u32 s10, s10, 0x10000
	s_addc_u32 s11, s11, 0
	global_load_dword v54, v34, s[10:11] nt
	s_add_u32 s10, s10, 0x10000
	s_addc_u32 s11, s11, 0
	global_load_dword v55, v34, s[10:11] nt
	s_mul_i32 s12, s21, 2
	s_add_u32 s12, s12, s8
	s_cmp_ge_u32 s12, 0xb00
	s_cbranch_scc1 .Lcv_wf2_l1_p1_ld_done
; template <class Map>
; DI void conv_T(bf16_t* __restrict__ dst, const float* __restrict__ src, int K, int ldsrc, int nphys, Map map, const float* __restrict__ kscale, float* tile) {
;     ...
;     for (int i = 0; i < 8; ++i) { const int kk = i * 8 + (tid >> 6);
;       float v = sc >= 0 ? __builtin_nontemporal_load(&src[(size_t)(k0 + kk) * ldsrc + sc]) : 0.f;
;       if (kscale) v *= kscale[k0 + kk];
;       tile[kk * 65 + nn] = v; }
;     __syncthreads();
;     const int np = tid >> 3, ks = tid & 7;
;     float v[8];
; #pragma unroll
;     for (int j = 0; j < 8; ++j) v[j] = tile[(ks * 8 + j) * 65 + np];
	s_mul_i32 s12, s21, 2
	s_add_u32 s12, s12, s8
	s_lshr_b32 s13, s12, 5
	s_and_b32 s14, s12, 31
	s_mul_i32 s15, s13, 0x80000
	s_lshl_b32 s16, s14, 8
	s_add_u32 s15, s15, s16
	s_add_u32 s10, s4, s15
	s_addc_u32 s11, s5, 0
	global_load_dword v56, v34, s[10:11] nt
	s_add_u32 s10, s10, 0x10000
	s_addc_u32 s11, s11, 0
	global_load_dword v57, v34, s[10:11] nt
	s_add_u32 s10, s10, 0x10000
	s_addc_u32 s11, s11, 0
	global_load_dword v58, v34, s[10:11] nt
	s_add_u32 s10, s10, 0x10000
	s_addc_u32 s11, s11, 0
	global_load_dword v59, v34, s[10:11] nt
	s_add_u32 s10, s10, 0x10000
	s_addc_u32 s11, s11, 0
	global_load_dword v60, v34, s[10:11] nt
	s_add_u32 s10, s10, 0x10000
	s_addc_u32 s11, s11, 0
	global_load_dword v61, v34, s[10:11] nt
	s_add_u32 s10, s10, 0x10000
	s_addc_u32 s11, s11, 0
	global_load_dword v62, v34, s[10:11] nt
	s_add_u32 s10, s10, 0x10000
	s_addc_u32 s11, s11, 0
	global_load_dword v63, v34, s[10:11] nt
	s_mul_i32 s12, s21, 3
	s_add_u32 s12, s12, s8
	s_cmp_ge_u32 s12, 0xb00
	s_cbranch_scc1 .Lcv_wf2_l1_p1_ld_done
	s_mul_i32 s12, s21, 3
	s_add_u32 s12, s12, s8
	s_lshr_b32 s13, s12, 5
	s_and_b32 s14, s12, 31
	s_mul_i32 s15, s13, 0x80000
	s_lshl_b32 s16, s14, 8
	s_add_u32 s15, s15, s16
	s_add_u32 s10, s4, s15
	s_addc_u32 s11, s5, 0
	global_load_dword v64, v34, s[10:11] nt
	s_add_u32 s10, s10, 0x10000
	s_addc_u32 s11, s11, 0
	global_load_dword v65, v34, s[10:11] nt
	s_add_u32 s10, s10, 0x10000
	s_addc_u32 s11, s11, 0
	global_load_dword v66, v34, s[10:11] nt
	s_add_u32 s10, s10, 0x10000
	s_addc_u32 s11, s11, 0
	global_load_dword v67, v34, s[10:11] nt
	s_add_u32 s10, s10, 0x10000
	s_addc_u32 s11, s11, 0
	global_load_dword v68, v34, s[10:11] nt
	s_add_u32 s10, s10, 0x10000
	s_addc_u32 s11, s11, 0
	global_load_dword v69, v34, s[10:11] nt
	s_add_u32 s10, s10, 0x10000
	s_addc_u32 s11, s11, 0
	global_load_dword v70, v34, s[10:11] nt
	s_add_u32 s10, s10, 0x10000
	s_addc_u32 s11, s11, 0
	global_load_dword v71, v34, s[10:11] nt
.Lcv_wf2_l1_p1_ld_done:
	s_waitcnt vmcnt(0)
	ds_write_b32 v31, v40
	ds_write_b32 v31, v41 offset:2080
	ds_write_b32 v31, v42 offset:4160
	ds_write_b32 v31, v43 offset:6240
	ds_write_b32 v31, v44 offset:8320
	ds_write_b32 v31, v45 offset:10400
	ds_write_b32 v31, v46 offset:12480
	ds_write_b32 v31, v47 offset:14560
	s_mul_i32 s12, s21, 1
	s_add_u32 s12, s12, s8
	s_cmp_ge_u32 s12, 0xb00
	s_cbranch_scc1 .Lcv_wf2_l1_p1_wr_done
	ds_write_b32 v31, v48 offset:16640
	ds_write_b32 v31, v49 offset:18720
	ds_write_b32 v31, v50 offset:20800
	ds_write_b32 v31, v51 offset:22880
	ds_write_b32 v31, v52 offset:24960
	ds_write_b32 v31, v53 offset:27040
	ds_write_b32 v31, v54 offset:29120
	ds_write_b32 v31, v55 offset:31200
	s_mul_i32 s12, s21, 2
	s_add_u32 s12, s12, s8
	s_cmp_ge_u32 s12, 0xb00
	s_cbranch_scc1 .Lcv_wf2_l1_p1_wr_done
	ds_write_b32 v31, v56 offset:33280
	ds_write_b32 v31, v57 offset:35360
	ds_write_b32 v31, v58 offset:37440
	ds_write_b32 v31, v59 offset:39520
	ds_write_b32 v31, v60 offset:41600
	ds_write_b32 v31, v61 offset:43680
	ds_write_b32 v31, v62 offset:45760
	ds_write_b32 v31, v63 offset:47840
	s_mul_i32 s12, s21, 3
	s_add_u32 s12, s12, s8
	s_cmp_ge_u32 s12, 0xb00
	s_cbranch_scc1 .Lcv_wf2_l1_p1_wr_done
	ds_write_b32 v31, v64 offset:49920
	ds_write_b32 v31, v65 offset:52000
	ds_write_b32 v31, v66 offset:54080
	ds_write_b32 v31, v67 offset:56160
	ds_write_b32 v31, v68 offset:58240
	ds_write_b32 v31, v69 offset:60320
	ds_write_b32 v31, v70 offset:62400
	ds_write_b32 v31, v71 offset:64480
.Lcv_wf2_l1_p1_wr_done:
	s_waitcnt lgkmcnt(0)
	s_barrier
	ds_read_b32 v40, v33
	ds_read_b32 v41, v33 offset:260
	ds_read_b32 v42, v33 offset:520
	ds_read_b32 v43, v33 offset:780
	ds_read_b32 v44, v33 offset:1040
	ds_read_b32 v45, v33 offset:1300
	ds_read_b32 v46, v33 offset:1560
	ds_read_b32 v47, v33 offset:1820
	s_mul_i32 s12, s21, 1
	s_add_u32 s12, s12, s8
	s_cmp_ge_u32 s12, 0xb00
	s_cbranch_scc1 .Lcv_wf2_l1_p1_rd_done
	ds_read_b32 v48, v33 offset:16640
	ds_read_b32 v49, v33 offset:16900
	ds_read_b32 v50, v33 offset:17160
	ds_read_b32 v51, v33 offset:17420
	ds_read_b32 v52, v33 offset:17680
	ds_read_b32 v53, v33 offset:17940
	ds_read_b32 v54, v33 offset:18200
	ds_read_b32 v55, v33 offset:18460
	s_mul_i32 s12, s21, 2
	s_add_u32 s12, s12, s8
	s_cmp_ge_u32 s12, 0xb00
	s_cbranch_scc1 .Lcv_wf2_l1_p1_rd_done
	ds_read_b32 v56, v33 offset:33280
	ds_read_b32 v57, v33 offset:33540
	ds_read_b32 v58, v33 offset:33800
	ds_read_b32 v59, v33 offset:34060
	ds_read_b32 v60, v33 offset:34320
	ds_read_b32 v61, v33 offset:34580
	ds_read_b32 v62, v33 offset:34840
	ds_read_b32 v63, v33 offset:35100
	s_mul_i32 s12, s21, 3
	s_add_u32 s12, s12, s8
	s_cmp_ge_u32 s12, 0xb00
	s_cbranch_scc1 .Lcv_wf2_l1_p1_rd_done
	ds_read_b32 v64, v33 offset:49920
	ds_read_b32 v65, v33 offset:50180
	ds_read_b32 v66, v33 offset:50440
	ds_read_b32 v67, v33 offset:50700
	ds_read_b32 v68, v33 offset:50960
	ds_read_b32 v69, v33 offset:51220
	ds_read_b32 v70, v33 offset:51480
	ds_read_b32 v71, v33 offset:51740

; DI unsigned cvtpk(float lo, float hi) { unsigned r; asm volatile("v_cvt_pk_bf16_f32 %0, %1, %2" : "=v"(r) : "v"(lo), "v"(hi)); return r; }
; DI int ltid() { int t = threadIdx.x; asm volatile("" : "+v"(t)); return t; }
; DI int lbid() { int b = blockIdx.x; asm volatile("" : "+s"(b)); return b; }
; template <class Map>
; DI void conv_T(bf16_t* __restrict__ dst, const float* __restrict__ src, int K, int ldsrc, int nphys, Map map, const float* __restrict__ kscale, float* tile) {
;   const int tid = ltid(), ntn = nphys >> 6, ntiles = (K >> 6) * ntn;
;   for (int tl = lbid(); tl < ntiles; tl += gridDim.x) {
;     const int k0 = (tl / ntn) << 6, n0 = (tl % ntn) << 6;
;     const int nn = tid & 63, sc = map(n0 + nn);
; #pragma unroll
;     for (int i = 0; i < 8; ++i) { const int kk = i * 8 + (tid >> 6);
;       float v = sc >= 0 ? __builtin_nontemporal_load(&src[(size_t)(k0 + kk) * ldsrc + sc]) : 0.f;
;       if (kscale) v *= kscale[k0 + kk];
;       tile[kk * 65 + nn] = v; }
;     __syncthreads();
;     const int np = tid >> 3, ks = tid & 7;
;     float v[8];
; #pragma unroll
;     for (int j = 0; j < 8; ++j) v[j] = tile[(ks * 8 + j) * 65 + np];
;     u32x4 w = {cvtpk(v[0], v[1]), cvtpk(v[2], v[3]), cvtpk(v[4], v[5]), cvtpk(v[6], v[7])};
;     *(u32x4*)(dst + (size_t)(n0 + np) * K + k0 + ks * 8) = w;
;     __syncthreads();
;   }
; DI void convert_layer(const Params& p, int l, float* tile) {
;     ...
;   conv_T((bf16_t*)(ws + O_WMISC), p.w_in + (size_t)l * 2048 * NIN, 2048, NIN, 256, MapMisc{}, nullptr, tile);
.Lcv_wf2_l1_p1_st_done:
	s_lshl_b32 s12, s21, 2
	s_add_u32 s8, s8, s12
	s_cmp_ge_u32 s8, 0xb00
	s_cbranch_scc0 .Lcv_wf2_l1_loop
.Lcv_wf2_l1_end:
	s_waitcnt lgkmcnt(0)
	s_barrier
.LBB0_2136:
	v_mov_b32_e32 v0, v248
	s_mov_b32 s4, s85
	s_cmpk_gt_i32 s4, 0x7f
	s_cbranch_scc1 .LBB0_2143
	v_and_b32_e32 v4, 63, v0
	v_ashrrev_i32_e32 v5, 6, v0
	v_ashrrev_i32_e32 v6, 3, v0
	v_lshlrev_b32_e32 v0, 3, v0
	v_and_b32_e32 v0, 56, v0
	v_lshl_add_u32 v2, v4, 2, 0
	v_lshl_add_u32 v3, v6, 2, 0
	v_mul_u32_u24_e32 v7, 0x104, v0
	v_mul_lo_u32 v8, v5, s28
	v_readlane_b32 s0, v251, 63
	s_lshl_b32 s5, s4, 6
	s_lshl_b32 s6, s0, 6
	v_add_u32_e32 v7, v3, v7
	v_lshlrev_b32_e32 v0, 1, v0
	v_add_u32_e32 v8, v2, v8
	v_readlane_b32 s1, v252, 0
	s_branch .LBB0_2139

; DI void convert_layer(const Params& p, int l, float* tile) {
;     ...
;   for (int r = 0; r < 3; ++r)
;     conv_T((bf16_t*)(ws + O_WBR) + (size_t)r * 2048 * 1024, p.w_br + (size_t)(l * 3 + r) * 1024 * 2048, 1024, 2048, 2048, MapId{0}, nullptr, tile);
;   conv_T((bf16_t*)(ws + O_WO), p.w_o + (size_t)l * 2048 * 2048, 2048, 2048, 2048, MapId{0}, nullptr, tile);
;   conv_T((bf16_t*)(ws + O_WF1), p.w_f1 + (size_t)l * 2048 * 2 * DFF, 2048, 2 * DFF, 2 * DFF, MapF1{}, nullptr, tile);
;   conv_T((bf16_t*)(ws + O_WF2), p.w_f2 + (size_t)l * DFF * 2048, DFF, 2048, 2048, MapId{0}, nullptr, tile);
; __global__ void __launch_bounds__(NTHR) fwd_megakernel(Params p) {
;     ...
;     if (l == 0) { xcd_barrier(xb); convert_layer(p, 1, (float*)lds); xcd_barrier(xb); }
.LBB0_2196:
.LBB0_2238:
	s_waitcnt vmcnt(0)
	s_barrier
	s_mov_b64 s[0:1], exec
	v_readlane_b32 s2, v249, 46
	v_readlane_b32 s3, v249, 47
	s_and_b64 s[2:3], s[0:1], s[2:3]
	s_mov_b64 exec, s[2:3]
	s_cbranch_execnz .LBB0_2239
	s_getpc_b64 s[98:99]
